# scan phase: T=(I-A)^-1 helper wave + f32-MFMA consumer, P1 raw-row loads issued a full iteration ahead, roles remapped across SIMDs
# speedup vs baseline: 1.0298x; 1.0298x over previous
; #define LAS __attribute__((address_space(3)))
; __device__ __forceinline__ void scan_phase(LAS unsigned char* lds, const bf16_t* R, const bf16_t* Kb, const bf16_t* V, const bf16_t* WA, const float* k_k, const float* k_a, bf16_t* Y, int G, int bid, int tid) {
;     const int wave = __builtin_amdgcn_readfirstlane(tid >> 6), lane = tid & 63, c = lane & 15, g = lane >> 4;
;     const int wq = (wave & 1) + ((wave >> 2) << 1);
;     const int pid = wq * 64 + lane, pt = (pid >> 4) & 15, pj = pid & 15;
;     const int pid1 = tid - 256, pta = (pid1 >> 4) & 7, ptb = pta + 8;
;     const bool producer = (wave == 2) || (wave == 3) || (wave >= 6), producer1 = (wave == 4) || (wave == 5), consumer = wave < 2;
;     constexpr int NCH = T / 16;
;     for (int unit = bid; unit < 256; unit += G) {
;         const int b = unit >> 5, h = (unit >> 1) & 15, half = unit & 1;
;         const size_t rowbase = (size_t)b * T;
;         f32x4 kkw = (f32x4){0.f, 0.f, 0.f, 0.f}, kaw = kkw;
;         if (producer1) { kkw = *(const f32x4*)(k_k + h * 64 + 4 * pj); kaw = *(const f32x4*)(k_a + h * 64 + 4 * pj); }
;         u32x2 rkA = (u32x2){0u, 0u}, rrA = rkA, raA = rkA, rlA = rkA, rkB = rkA, rrB = rkA, raB = rkA, rlB = rkA; unsigned rvA = 0u, rvB = 0u;
.LBB0_873:
	v_readlane_b32 s2, v254, 1
	v_readlane_b32 s3, v254, 2
	s_cmp_lt_i32 s2, 11
	s_cselect_b64 s[2:3], -1, 0
	s_and_b64 s[4:5], s[2:3], s[0:1]
	s_andn2_b64 vcc, exec, s[4:5]
	s_cbranch_vccnz .LBB0_952
	v_mbcnt_lo_u32_b32 v1, -1, 0
	v_mbcnt_hi_u32_b32 v1, -1, v1
	s_lshr_b32 s98, s52, 4
	s_lshr_b32 s98, 0x76325410, s98
	s_and_b32 s98, s98, 7
	s_lshl_b32 s98, s98, 6
	s_cmpk_gt_i32 s84, 0xff
	v_add_u32_e32 v2, s98, v1
	s_mov_b64 s[0:1], s[82:83]
	v_readfirstlane_b32 s2, v2
	s_cbranch_scc1 .LBB0_952
	v_writelane_b32 v254, s4, 4
	v_and_b32_e32 v4, 63, v1
	v_and_b32_e32 v6, 15, v1
	v_writelane_b32 v254, s5, 5
	s_load_dwordx4 s[56:59], s[0:1], 0xc0
	s_load_dwordx4 s[4:7], s[0:1], 0x78
	v_writelane_b32 v254, s82, 6
	v_bfe_u32 v98, v2, 4, 3
	v_lshlrev_b32_e32 v2, 2, v2
	s_waitcnt lgkmcnt(0)
	s_add_u32 s64, s58, 0x16000000
	s_addc_u32 s65, s59, 0
	s_add_u32 s66, s56, 0x4000000
	s_addc_u32 s67, s57, 0
	s_add_u32 s68, s58, 0x8000000
	s_addc_u32 s69, s59, 0
	s_ashr_i32 s10, s2, 6
	s_and_b32 s3, s2, 0xffffff80
	s_cmpk_eq_i32 s3, 0x80
	s_cselect_b64 s[0:1], -1, 0
	s_cmp_gt_i32 s10, 5
	s_cselect_b64 s[8:9], -1, 0
	s_or_b64 s[70:71], s[0:1], s[8:9]
	s_cmpk_eq_i32 s3, 0x100
	s_cselect_b64 s[72:73], -1, 0
	s_cmpk_lg_i32 s3, 0x100
	v_writelane_b32 v254, s83, 7
	s_cselect_b64 s[0:1], -1, 0
	s_cmp_lt_i32 s10, 2
	v_writelane_b32 v254, s0, 8
	s_cselect_b64 s[76:77], -1, 0
	s_ashr_i32 s8, s2, 7
	v_writelane_b32 v254, s1, 9
	s_and_b32 s0, s10, 1
	s_and_b32 s1, s8, -2
	s_or_b32 s30, s0, s1
	s_mul_i32 s0, s10, 0xa00
	v_lshl_or_b32 v0, s30, 6, v4
	s_add_i32 s33, s0, 0
	s_lshl_b32 s0, s10, 4
	v_bfe_u32 v5, v0, 4, 4
	v_mov_b32_e32 v0, 0
	s_lshl_b32 s31, s30, 2
	s_ashr_i32 s1, s0, 31
	v_and_b32_e32 v103, 0x1fc, v2
	v_lshlrev_b32_e32 v2, 3, v6
	v_mov_b32_e32 v3, v0
	s_cmp_gt_i32 s8, -1
	v_lshl_add_u64 v[112:113], s[56:57], 0, v[2:3]
	v_lshl_add_u64 v[114:115], s[64:65], 0, v[2:3]
	v_lshlrev_b32_e32 v3, 4, v1
	s_cselect_b64 s[8:9], -1, 0
	s_cmp_lg_u32 s30, 0
	v_bfe_u32 v7, v1, 4, 2
	v_lshlrev_b32_e32 v102, 2, v6
	v_and_b32_e32 v165, 48, v3
	v_lshlrev_b32_e32 v3, 1, v1
	s_cselect_b64 s[82:83], -1, 0
	s_cmp_gt_i32 s30, 0
	v_and_b32_e32 v166, 8, v3
	v_or_b32_e32 v3, v102, v7
	s_mov_b32 s75, s84
	s_cselect_b64 s[84:85], -1, 0
	s_cmp_lt_u32 s31, 5
	v_mul_u32_u24_e32 v3, 40, v3
	s_cselect_b64 s[86:87], -1, 0
	s_cmp_gt_i32 s30, 1
	v_lshlrev_b32_e32 v104, 4, v6
	v_mov_b32_e32 v105, v0
	v_lshl_add_u32 v167, s30, 3, v3
	v_and_b32_e32 v171, 48, v1
	v_lshlrev_b32_e32 v3, 2, v7
	v_and_b32_e32 v1, 16, v1
	s_cselect_b64 s[88:89], -1, 0
	s_cmp_lt_u32 s31, 9
	v_lshl_add_u64 v[108:109], s[4:5], 0, v[104:105]
	v_cmp_eq_u32_e64 s[4:5], 0, v1
	s_cselect_b64 s[90:91], -1, 0
	s_cmp_gt_i32 s30, 2
	v_or_b32_e32 v1, 1, v3
	v_or_b32_e32 v100, 8, v98
	s_cselect_b64 s[92:93], -1, 0
	s_cmp_lt_u32 s31, 13
	v_cmp_lt_u32_e32 vcc, v1, v6
	v_or_b32_e32 v1, 2, v3
	v_lshlrev_b32_e32 v155, 6, v100
	v_lshlrev_b32_e32 v161, 8, v5
	s_cselect_b64 s[94:95], -1, 0
	v_cmp_lt_u32_e64 s[48:49], v1, v6
	v_cmp_gt_u32_e64 s[42:43], v1, v6
	v_or_b32_e32 v1, 3, v3
	s_add_i32 s51, 0, 0x13400
	v_cmp_lt_u32_e64 s[44:45], v1, v6
	v_cmp_gt_u32_e64 s[46:47], v1, v6
	v_add_u32_e32 v1, s51, v155
	v_add_u32_e32 v178, 0, v161
	s_movk_i32 s51, 0xff40
	s_movk_i32 s50, 0x50
	v_writelane_b32 v254, s8, 10
	v_mad_i32_i24 v179, v5, s51, v178
	v_lshl_add_u64 v[106:107], s[6:7], 0, v[104:105]
	v_lshlrev_b32_e32 v162, 6, v5
	v_mul_u32_u24_e32 v163, 0x90, v5
	v_lshlrev_b32_e32 v169, 1, v5
	v_cmp_eq_u32_e64 s[2:3], 15, v5
	v_cmp_gt_u32_e64 s[6:7], 32, v4
	v_writelane_b32 v254, s9, 11
	v_cmp_eq_u32_e64 s[8:9], 0, v5
	v_cmp_gt_u32_e64 s[10:11], 2, v5
	v_cmp_gt_u32_e64 s[12:13], 3, v5
	v_cmp_gt_u32_e64 s[14:15], 4, v5
	v_cmp_lt_u32_e64 s[16:17], 4, v5
	v_cmp_gt_u32_e64 s[18:19], 6, v5
	v_cmp_gt_u32_e64 s[20:21], 7, v5
	v_cmp_gt_u32_e64 s[22:23], 8, v5
	v_cmp_lt_u32_e64 s[24:25], 8, v5
	v_cmp_gt_u32_e64 s[26:27], 10, v5
	v_cmp_gt_u32_e64 s[28:29], 11, v5
	v_cmp_gt_u32_e64 s[30:31], 12, v5
	v_cmp_lt_u32_e64 s[34:35], 12, v5
	v_cmp_gt_u32_e64 s[36:37], 14, v5
	v_cmp_lt_u32_e64 s[38:39], v3, v6
	v_cmp_gt_u32_e64 s[40:41], v3, v6
	v_mad_u32_u24 v3, v5, s50, v179
	v_lshlrev_b32_e32 v4, 13, v7
	v_mov_b32_e32 v5, v0
	v_lshlrev_b32_e32 v110, 1, v6
	v_lshl_add_u64 v[4:5], s[0:1], 1, v[4:5]
	v_or_b32_e32 v4, v4, v110
	v_lshlrev_b32_e32 v9, 8, v7
	v_lshl_add_u64 v[116:117], s[58:59], 0, v[4:5]
	v_lshl_or_b32 v4, v98, 12, v2
	v_mov_b32_e32 v5, v0
	v_and_b32_e32 v164, 64, v2
	v_add3_u32 v172, s33, v9, v102
	v_or_b32_e32 v9, s0, v6
	v_lshl_add_u64 v[4:5], s[58:59], 0, v[4:5]
	s_mov_b64 s[0:1], 0x8038800
	v_mul_lo_u32 v173, v9, 40
	v_add3_u32 v9, v3, v164, v165
	v_lshlrev_b32_e32 v3, 6, v6
	v_lshl_add_u64 v[118:119], v[4:5], 0, s[0:1]
	v_lshlrev_b32_e32 v4, 11, v98
	v_lshl_or_b32 v99, v98, 8, v104
	v_lshl_or_b32 v105, v100, 8, v104
	v_mul_u32_u24_e32 v168, 0x50, v6
	v_mul_u32_u24_e32 v170, 0x90, v6
	v_mul_u32_u24_e32 v175, 40, v6
	v_mad_u32_u24 v180, v6, s50, 0
	v_sub_u32_e32 v6, 0, v3
	v_or_b32_e32 v2, v4, v2
	v_mov_b32_e32 v3, v0
	v_add_u32_e32 v101, 0, v99
	v_add_u32_e32 v111, 0, v105
	v_add_u32_e32 v8, 0, v155
	v_lshl_add_u64 v[120:121], s[56:57], 0, v[2:3]
	v_lshl_add_u64 v[122:123], s[58:59], 0, v[2:3]
	v_or_b32_e32 v2, v4, v102
	s_or_b64 s[48:49], s[44:45], s[48:49]
	s_mov_b32 s79, 0
	v_add_u32_e32 v160, 0, v104
	v_lshlrev_b32_e32 v174, 3, v7
	v_add_u32_e32 v176, 0xf400, v101
	v_add_u32_e32 v177, 0xf400, v111
	v_lshl_add_u64 v[124:125], s[56:57], 0, v[2:3]
	s_mov_b32 s74, 0x179abe15
	v_add_u32_e32 v181, v9, v166
	v_add_u32_e32 v181, 0x14000, v181
	v_add_u32_e32 v182, v180, v6
	v_add_u32_e32 v182, 0x14000, v182
	s_xor_b64 s[58:59], s[70:71], -1
	v_mov_b32_e32 v183, 0x5368d4a5
	v_add_u32_e32 v184, v8, v102
	v_add_u32_e32 v185, v1, v102
	s_or_b64 s[50:51], s[48:49], vcc
	v_writelane_b32 v254, s75, 12
	s_branch .LBB0_877

; __device__ __forceinline__ void scan_phase(LAS unsigned char* lds, const bf16_t* R, const bf16_t* Kb, const bf16_t* V, const bf16_t* WA, const float* k_k, const float* k_a, bf16_t* Y, int G, int bid, int tid) {
;     ...
;         if (producer1) { CK_LOAD(A, pta, 0); CK_LOAD(B, ptb, 0); CK_P1(A, pta, 0); CK_P1(B, ptb, 0); CK_LOAD(A, pta, 1); CK_LOAD(B, ptb, 1); }
;         f32x4 H[4];
; #pragma unroll
;         for (int kt = 0; kt < 4; ++kt) H[kt] = (f32x4){0.f, 0.f, 0.f, 0.f};
;         __syncthreads();
;         for (int it = 0; it <= NCH; ++it) {
;             if (producer1 && it + 1 < NCH) { CK_P1(A, pta, it + 1); CK_P1(B, ptb, it + 1); if (it + 2 < NCH) { CK_LOAD(A, pta, it + 2); CK_LOAD(B, ptb, it + 2); } }
.LBB0_884:
	s_and_b64 vcc, exec, s[52:53]
	s_waitcnt vmcnt(0) lgkmcnt(0)
	s_barrier
	s_cbranch_vccnz .LBB0_886
	v_lshlrev_b32_e32 v28, 16, v134
	v_and_b32_e32 v29, 0xffff0000, v134
	v_lshlrev_b32_e32 v30, 16, v135
	v_and_b32_e32 v31, 0xffff0000, v135
	v_pk_mul_f32 v[36:37], v[8:9], v[28:29]
	v_pk_mul_f32 v[38:39], v[10:11], v[30:31]
	v_pk_mul_f32 v[42:43], v[36:37], v[36:37]
	v_pk_mul_f32 v[40:41], v[38:39], v[38:39]
	v_lshlrev_b32_e32 v32, 16, v140
	v_and_b32_e32 v33, 0xffff0000, v140
	v_lshlrev_b32_e32 v34, 16, v141
	v_and_b32_e32 v35, 0xffff0000, v141
	v_pk_mov_b32 v[44:45], v[42:43], v[40:41] op_sel:[1,0]
	v_mov_b32_e32 v43, v41
	v_pk_add_f32 v[40:41], v[44:45], v[42:43]
	v_pk_add_f32 v[42:43], v[34:35], -1.0 op_sel_hi:[1,0]
	v_pk_add_f32 v[44:45], v[32:33], -1.0 op_sel_hi:[1,0]
	v_pk_fma_f32 v[42:43], v[6:7], v[42:43], 1.0 op_sel_hi:[1,1,0]
	v_pk_fma_f32 v[44:45], v[4:5], v[44:45], 1.0 op_sel_hi:[1,1,0]
	v_pk_mul_f32 v[30:31], v[42:43], v[30:31]
	v_pk_mul_f32 v[28:29], v[44:45], v[28:29]
	v_lshlrev_b32_e32 v24, 16, v136
	v_and_b32_e32 v25, 0xffff0000, v136
	v_lshlrev_b32_e32 v26, 16, v137
	v_and_b32_e32 v27, 0xffff0000, v137
	ds_write_b128 v176, v[28:31] offset:8192
	ds_write_b128 v176, v[24:27] offset:12288
	v_lshlrev_b32_e32 v30, 16, v126
	v_and_b32_e32 v31, 0xffff0000, v126
	v_lshlrev_b32_e32 v42, 16, v127
	v_and_b32_e32 v43, 0xffff0000, v127
	v_pk_mul_f32 v[48:49], v[8:9], v[30:31]
	v_pk_mul_f32 v[50:51], v[10:11], v[42:43]
	v_pk_mul_f32 v[28:29], v[48:49], v[48:49]
	v_pk_mul_f32 v[26:27], v[50:51], v[50:51]
	s_lshl_b64 s[62:63], s[78:79], 1
	v_pk_mov_b32 v[52:53], v[28:29], v[26:27] op_sel:[1,0]
	v_mov_b32_e32 v29, v27
	v_pk_add_f32 v[26:27], v[52:53], v[28:29]
	v_mov_b32_e32 v29, v40
	v_mov_b32_e32 v28, v26
	v_mov_b32_e32 v40, v27
	v_pk_add_f32 v[26:27], v[28:29], v[40:41]
	s_add_u32 s80, s66, s62
	s_addc_u32 s81, s67, s63
	v_mov_b32_dpp v29, v27 quad_perm:[1,0,3,2] row_mask:0xf bank_mask:0xf bound_ctrl:1
	v_mov_b32_dpp v28, v26 quad_perm:[1,0,3,2] row_mask:0xf bank_mask:0xf bound_ctrl:1
	v_pk_add_f32 v[26:27], v[26:27], v[28:29]
	s_lshl_b64 s[52:53], s[60:61], 1
	s_add_u32 s52, s80, s52
	v_mov_b32_dpp v29, v27 quad_perm:[2,3,0,1] row_mask:0xf bank_mask:0xf bound_ctrl:1
	v_mov_b32_dpp v28, v26 quad_perm:[2,3,0,1] row_mask:0xf bank_mask:0xf bound_ctrl:1
	v_pk_add_f32 v[26:27], v[26:27], v[28:29]
	s_addc_u32 s53, s81, s53
	v_mov_b32_e32 v13, v0
	v_mov_b32_dpp v29, v27 row_half_mirror row_mask:0xf bank_mask:0xf bound_ctrl:1
	v_mov_b32_dpp v28, v26 row_half_mirror row_mask:0xf bank_mask:0xf bound_ctrl:1
	v_pk_add_f32 v[26:27], v[26:27], v[28:29]
	v_add_u32_e32 v1, 0x13400, v22
	v_lshl_add_u64 v[16:17], s[52:53], 0, v[12:13]
	v_mov_b32_dpp v29, v27 row_mirror row_mask:0xf bank_mask:0xf bound_ctrl:1
	v_mov_b32_dpp v28, v26 row_mirror row_mask:0xf bank_mask:0xf bound_ctrl:1
	v_pk_add_f32 v[40:41], v[26:27], v[28:29]
	v_lshlrev_b32_e32 v12, 16, v138
	v_and_b32_e32 v13, 0xffff0000, v138
	v_lshlrev_b32_e32 v14, 16, v139
	v_and_b32_e32 v15, 0xffff0000, v139
	ds_write_b32 v1, v187
	ds_write_b128 v101, v[12:15] offset:35840
	v_rsq_f32_e32 v1, v41
	v_cmp_lt_f32_e64 s[52:53], s74, v41
	v_cmp_lt_f32_e32 vcc, s74, v40
	v_lshlrev_b32_e32 v44, 16, v132
	v_cndmask_b32_e64 v26, v183, v1, s[52:53]
	v_rsq_f32_e32 v1, v40
	v_pk_mul_f32 v[28:29], v[38:39], v[26:27] op_sel_hi:[1,0] neg_lo:[0,1] neg_hi:[0,1]
	v_pk_mul_f32 v[26:27], v[36:37], v[26:27] op_sel_hi:[1,0] neg_lo:[0,1] neg_hi:[0,1]
	ds_write_b128 v101, v[26:29] offset:62464
	v_pk_mul_f32 v[28:29], v[28:29], v[34:35] neg_lo:[1,0] neg_hi:[1,0]
	v_pk_mul_f32 v[26:27], v[26:27], v[32:33] neg_lo:[1,0] neg_hi:[1,0]
	ds_write_b128 v176, v[26:29] offset:4096
	v_cndmask_b32_e32 v26, v183, v1, vcc
	v_and_b32_e32 v45, 0xffff0000, v132
	v_lshlrev_b32_e32 v46, 16, v133
	v_and_b32_e32 v47, 0xffff0000, v133
	v_pk_mul_f32 v[28:29], v[50:51], v[26:27] op_sel_hi:[1,0] neg_lo:[0,1] neg_hi:[0,1]
	v_pk_mul_f32 v[26:27], v[48:49], v[26:27] op_sel_hi:[1,0] neg_lo:[0,1] neg_hi:[0,1]
	ds_write_b128 v111, v[26:29] offset:62464
	v_pk_mul_f32 v[28:29], v[28:29], v[46:47] neg_lo:[1,0] neg_hi:[1,0]
	v_pk_mul_f32 v[26:27], v[26:27], v[44:45] neg_lo:[1,0] neg_hi:[1,0]
	ds_write_b128 v177, v[26:29] offset:4096
	v_pk_add_f32 v[26:27], v[46:47], -1.0 op_sel_hi:[1,0]
	v_pk_add_f32 v[28:29], v[44:45], -1.0 op_sel_hi:[1,0]
	v_pk_fma_f32 v[26:27], v[6:7], v[26:27], 1.0 op_sel_hi:[1,1,0]
	v_pk_fma_f32 v[32:33], v[4:5], v[28:29], 1.0 op_sel_hi:[1,1,0]
	v_lshlrev_b32_e32 v12, 16, v130
	v_and_b32_e32 v13, 0xffff0000, v130
	v_pk_mul_f32 v[28:29], v[26:27], v[42:43]
	v_pk_mul_f32 v[26:27], v[32:33], v[30:31]
	s_or_b32 s0, s0, 32
	v_lshlrev_b32_e32 v14, 16, v131
	v_and_b32_e32 v15, 0xffff0000, v131
	v_lshlrev_b32_e32 v22, 16, v128
	v_and_b32_e32 v23, 0xffff0000, v128
	v_lshlrev_b32_e32 v24, 16, v129
	v_and_b32_e32 v25, 0xffff0000, v129
	ds_write_b128 v177, v[26:29] offset:8192
	ds_write_b128 v177, v[22:25] offset:12288
	ds_write_b32 v185, v186
	ds_write_b128 v111, v[12:15] offset:35840
	v_mov_b32_e32 v13, s1
	v_or_b32_e32 v12, s0, v98
	v_lshlrev_b64 v[14:15], 11, v[12:13]
	v_lshlrev_b64 v[12:13], 12, v[12:13]
	v_lshl_add_u64 v[20:21], v[112:113], 0, s[62:63]
	v_lshl_add_u64 v[12:13], s[68:69], 0, v[12:13]
	v_lshl_add_u64 v[18:19], v[114:115], 0, s[62:63]
	v_lshl_add_u64 v[22:23], v[20:21], 0, v[14:15]
	v_lshl_add_u64 v[12:13], v[12:13], 0, s[62:63]
	v_mov_b32_e32 v3, v0
	global_load_dwordx2 v[188:189], v[22:23], off
	v_lshl_add_u64 v[22:23], v[18:19], 0, v[14:15]
	v_lshl_add_u64 v[12:13], v[12:13], 0, v[2:3]
	global_load_dwordx2 v[190:191], v[22:23], off
	global_load_dwordx2 v[192:193], v[12:13], off
	global_load_dwordx2 v[194:195], v[12:13], off offset:2048
	v_lshl_add_u64 v[12:13], v[16:17], 0, v[14:15]
	global_load_dword v196, v[12:13], off
	v_mov_b32_e32 v13, s1
	v_or_b32_e32 v12, s0, v100
	v_lshlrev_b64 v[14:15], 11, v[12:13]
	v_lshlrev_b64 v[12:13], 12, v[12:13]
	v_lshl_add_u64 v[12:13], s[68:69], 0, v[12:13]
	v_lshl_add_u64 v[12:13], v[12:13], 0, s[62:63]
	v_lshl_add_u64 v[20:21], v[20:21], 0, v[14:15]
	v_lshl_add_u64 v[18:19], v[18:19], 0, v[14:15]
	v_lshl_add_u64 v[2:3], v[12:13], 0, v[2:3]
	global_load_dwordx2 v[198:199], v[20:21], off
	global_load_dwordx2 v[200:201], v[18:19], off
	global_load_dwordx2 v[202:203], v[2:3], off
	global_load_dwordx2 v[204:205], v[2:3], off offset:2048
	v_lshl_add_u64 v[2:3], v[16:17], 0, v[14:15]
	global_load_dword v197, v[2:3], off

; __device__ __forceinline__ void scan_phase(LAS unsigned char* lds, const bf16_t* R, const bf16_t* Kb, const bf16_t* V, const bf16_t* WA, const float* k_k, const float* k_a, bf16_t* Y, int G, int bid, int tid) {
;     ...
;                 const f32x4 Gm = Gc - lf;
;                 f32x4 eA, eR, eN;
; #pragma unroll
;                 for (int e = 0; e < 4; ++e) { eA[e] = __expf(Gm[e]); eR[e] = __expf(Gc[e]); eN[e] = __expf(-Gc[e]); }
;                 const f32x4 ab = nkk * eA, rb = rf * eR, bt = be * eN, kt_ = kp * eN;
;                 const unsigned ab0 = ck_cvt(ab.x, ab.y), ab1 = ck_cvt(ab.z, ab.w), rb0 = ck_cvt(rb.x, rb.y), rb1 = ck_cvt(rb.z, rb.w);
;                 const unsigned bt0 = ck_cvt(bt.x, bt.y), bt1 = ck_cvt(bt.z, bt.w), kt0 = ck_cvt(kt_.x, kt_.y), kt1 = ck_cvt(kt_.z, kt_.w);
;                 LAS unsigned char* rowp = buf + pt * CK_RP + 64 * (pj >> 3) + 16 * (pj & 3) + 8 * ((pj >> 2) & 1);
;                 *(LAS u32x2*)(rowp + CK_ABAR) = (u32x2){ab0, ab1}; *(LAS u32x2*)(rowp + CK_RBAR) = (u32x2){rb0, rb1};
;                 *(LAS u32x2*)(rowp + CK_BTIL) = (u32x2){bt0, bt1}; *(LAS u32x2*)(rowp + CK_KTIL) = (u32x2){kt0, kt1};
;                 constexpr int TS = CK_TP / 2;
;                 {
;                     const int rrow = lane >> 4;
;     ...
;                     unsigned b0_ = __float_as_uint(bt.x), b1_ = __float_as_uint(bt.y), b2_ = __float_as_uint(bt.z), b3_ = __float_as_uint(bt.w);
;                     unsigned k0_ = __float_as_uint(kt_.x), k1_ = __float_as_uint(kt_.y), k2_ = __float_as_uint(kt_.z), k3_ = __float_as_uint(kt_.w);
;                     CK_T4(b0_, b1_, b2_, b3_); CK_T4(k0_, k1_, k2_, k3_);
;     ...
;                     const int toff = (4 * pj + rrow) * CK_TP + 8 * wq;
;                     *(LAS u32x2*)(buf + CK_BT_T + toff) = (u32x2){ck_cvt(__uint_as_float(b0_), __uint_as_float(b1_)), ck_cvt(__uint_as_float(b2_), __uint_as_float(b3_))};
;                     *(LAS u32x2*)(buf + CK_KT_T + toff) = (u32x2){ck_cvt(__uint_as_float(k0_), __uint_as_float(k1_)), ck_cvt(__uint_as_float(k2_), __uint_as_float(k3_))};
;                 }
;                 LAS unsigned short* vT = (LAS unsigned short*)(buf + CK_VT + (2 * pj) * CK_TP + pt * 2);
;                 vT[0] = (unsigned short)(vsave & 0xffffu); vT[TS] = (unsigned short)(vsave >> 16);
;                 if (pt == 15) *(LAS f32x4*)(buf + CK_GAM + 16 * pj) = eR;
.LBB0_911:
	v_sub_f32_e32 v1, v35, v31
	v_sub_f32_e32 v30, v34, v30
	v_sub_f32_e32 v3, v33, v29
	v_mul_f32_e32 v29, 0xbfb8aa3b, v32
	v_mul_f32_e32 v31, 0xbfb8aa3b, v33
	v_mul_f32_e32 v1, 0x3fb8aa3b, v1
	v_sub_f32_e32 v2, v32, v28
	v_mul_f32_e32 v28, 0x3fb8aa3b, v32
	v_exp_f32_e32 v32, v29
	v_mul_f32_e32 v29, 0x3fb8aa3b, v33
	v_exp_f32_e32 v33, v31
	v_mul_f32_e32 v30, 0x3fb8aa3b, v30
	v_mul_f32_e32 v31, 0xbfb8aa3b, v34
	v_exp_f32_e32 v37, v1
	v_mul_f32_e32 v1, 0x3fb8aa3b, v35
	v_mul_f32_e32 v2, 0x3fb8aa3b, v2
	v_mul_f32_e32 v3, 0x3fb8aa3b, v3
	v_exp_f32_e32 v36, v30
	v_mul_f32_e32 v30, 0x3fb8aa3b, v34
	v_exp_f32_e32 v34, v31
	v_exp_f32_e32 v31, v1
	v_mul_f32_e32 v1, 0xbfb8aa3b, v35
	v_exp_f32_e32 v2, v2
	v_exp_f32_e32 v28, v28
	v_exp_f32_e32 v3, v3
	v_exp_f32_e32 v29, v29
	v_exp_f32_e32 v30, v30
	v_exp_f32_e32 v35, v1
	v_pk_mul_f32 v[26:27], v[26:27], v[36:37]
	v_pk_mul_f32 v[2:3], v[24:25], v[2:3]
	v_pk_mul_f32 v[22:23], v[22:23], v[30:31]
	v_pk_mul_f32 v[20:21], v[20:21], v[28:29]
	v_pk_mul_f32 v[18:19], v[18:19], v[34:35]
	v_pk_mul_f32 v[16:17], v[16:17], v[32:33]
	v_pk_mul_f32 v[14:15], v[14:15], v[34:35]
	v_pk_mul_f32 v[12:13], v[12:13], v[32:33]
	v_cvt_pk_bf16_f32 v2, v2, v3
	v_cvt_pk_bf16_f32 v3, v26, v27
	v_cvt_pk_bf16_f32 v20, v20, v21
	v_cvt_pk_bf16_f32 v21, v22, v23
	v_cvt_pk_bf16_f32 v22, v16, v17
	v_cvt_pk_bf16_f32 v23, v18, v19
	v_permlane32_swap_b32_e32 v17, v19
	v_cvt_pk_bf16_f32 v24, v12, v13
	v_cvt_pk_bf16_f32 v25, v14, v15
	ds_write_b64 v181, v[2:3]
	ds_write_b64 v181, v[20:21] offset:2304
	ds_write_b64 v181, v[22:23] offset:4608
	ds_write_b64 v181, v[24:25] offset:6912
	v_permlane32_swap_b32_e32 v16, v18
	v_mov_b32_e32 v1, v17
	v_mov_b32_e32 v3, v19
	v_permlane32_swap_b32_e32 v12, v14
	v_permlane32_swap_b32_e32 v13, v15
	v_permlane16_swap_b32_e32 v16, v1
	v_permlane16_swap_b32_e32 v18, v3
	v_permlane16_swap_b32_e32 v12, v13
	v_permlane16_swap_b32_e32 v14, v15
	v_cvt_pk_bf16_f32 v2, v16, v1
	v_cvt_pk_bf16_f32 v3, v18, v3
	v_add_u32_e32 v1, 0x14000, v167
	v_cvt_pk_bf16_f32 v12, v12, v13
	v_cvt_pk_bf16_f32 v13, v14, v15
	ds_write2st64_b64 v1, v[2:3], v[12:13] offset0:18 offset1:23
	v_add_u32_e32 v1, v180, v169
	v_add_u32_e32 v1, 0x14000, v1
	ds_write_b16 v1, v56 offset:14336
	ds_write_b16_d16_hi v1, v56 offset:14376
	s_and_saveexec_b64 s[0:1], s[2:3]
	ds_write_b128 v182, v[28:31] offset:15616
	s_or_b64 exec, exec, s[0:1]

.LBB0_915:
	s_add_u32 s60, s60, 0x8000
	s_addc_u32 s61, s61, 0
	s_mov_b64 s[0:1], 0x10000
	v_lshl_add_u64 v[144:145], v[144:145], 0, s[0:1]
	s_cmp_eq_u32 s60, 0x808000
	s_mov_b32 s63, s62
	s_waitcnt lgkmcnt(0)
	s_barrier
	s_cbranch_scc1 .LBB0_876

; __device__ __forceinline__ void scan_phase(LAS unsigned char* lds, const bf16_t* R, const bf16_t* Kb, const bf16_t* V, const bf16_t* WA, const float* k_k, const float* k_a, bf16_t* Y, int G, int bid, int tid) {
;     ...
;         if (producer1) { CK_LOAD(A, pta, 0); CK_LOAD(B, ptb, 0); CK_P1(A, pta, 0); CK_P1(B, ptb, 0); CK_LOAD(A, pta, 1); CK_LOAD(B, ptb, 1); }
;         f32x4 H[4];
; #pragma unroll
;         for (int kt = 0; kt < 4; ++kt) H[kt] = (f32x4){0.f, 0.f, 0.f, 0.f};
;         __syncthreads();
;         for (int it = 0; it <= NCH; ++it) {
;             if (producer1 && it + 1 < NCH) { CK_P1(A, pta, it + 1); CK_P1(B, ptb, it + 1); if (it + 2 < NCH) { CK_LOAD(A, pta, it + 2); CK_LOAD(B, ptb, it + 2); } }
.LBB0_918:
	s_andn2_b64 vcc, exec, s[0:1]
	s_cbranch_vccnz .LBB0_921
	s_waitcnt vmcnt(0)
	v_mov_b64_e32 v[134:135], v[188:189]
	v_mov_b64_e32 v[136:137], v[190:191]
	v_mov_b64_e32 v[138:139], v[192:193]
	v_mov_b64_e32 v[140:141], v[194:195]
	v_mov_b32_e32 v187, v196
	v_mov_b64_e32 v[126:127], v[198:199]
	v_mov_b64_e32 v[128:129], v[200:201]
	v_mov_b64_e32 v[130:131], v[202:203]
	v_mov_b64_e32 v[132:133], v[204:205]
	v_mov_b32_e32 v186, v197
	s_cmp_eq_u32 s60, 0x7e8000
	s_cbranch_scc1 .Lmy_p1_noload
	v_lshl_add_u64 v[2:3], v[146:147], 0, s[60:61]
	v_add_co_u32_e32 v28, vcc, 0x18000, v2
	s_nop 1
	v_addc_co_u32_e32 v29, vcc, 0, v3, vcc
	global_load_dwordx2 v[188:189], v[28:29], off
	v_lshl_add_u64 v[28:29], v[148:149], 0, s[60:61]
	v_add_co_u32_e32 v30, vcc, 0x16018000, v28
	s_nop 1
	v_addc_co_u32_e32 v31, vcc, 0, v29, vcc
	global_load_dwordx2 v[190:191], v[30:31], off
	v_add_co_u32_e32 v30, vcc, 0xffff8000, v144
	s_nop 1
	v_addc_co_u32_e32 v31, vcc, -1, v145, vcc
	global_load_dwordx2 v[192:193], v[30:31], off offset:-2048
	global_load_dwordx2 v[194:195], v[30:31], off
	v_lshl_add_u64 v[30:31], v[150:151], 0, s[60:61]
	v_add_co_u32_e32 v32, vcc, 0x4018000, v30
	s_nop 1
	v_addc_co_u32_e32 v33, vcc, 0, v31, vcc
	v_add_co_u32_e32 v2, vcc, 0x1c000, v2
	s_nop 1
	v_addc_co_u32_e32 v3, vcc, 0, v3, vcc
	global_load_dword v196, v[32:33], off
	global_load_dwordx2 v[198:199], v[2:3], off
	v_add_co_u32_e32 v2, vcc, 0x1601c000, v28
	s_nop 1
	v_addc_co_u32_e32 v3, vcc, 0, v29, vcc
	global_load_dwordx2 v[200:201], v[2:3], off
	global_load_dwordx2 v[202:203], v[144:145], off offset:-2048
	global_load_dwordx2 v[204:205], v[144:145], off
	v_add_co_u32_e32 v2, vcc, 0x401c000, v30
	s_nop 1
	v_addc_co_u32_e32 v3, vcc, 0, v31, vcc
	global_load_dword v197, v[2:3], off
; #define LAS __attribute__((address_space(3)))
; __device__ __forceinline__ void scan_phase(LAS unsigned char* lds, const bf16_t* R, const bf16_t* Kb, const bf16_t* V, const bf16_t* WA, const float* k_k, const float* k_a, bf16_t* Y, int G, int bid, int tid) {
;     ...
;             if (producer && it < NCH) {
;                 LAS unsigned char* buf = lds + (it & 1) * CK_BUF;
;                 const LAS unsigned char* ldp = lds + CK_LD + (it & 1) * 4096 + 16 * pj;
;                 const LAS unsigned char* stp = lds + CK_STG + (it & 1) * CK_STG_SZ + (pt * 64 + 4 * pj) * 4;
;                 f32x4 nkk = *(const LAS f32x4*)(stp), be = *(const LAS f32x4*)(stp + 4096), kp = *(const LAS f32x4*)(stp + 8192), rf = *(const LAS f32x4*)(stp + 12288), lf = *(const LAS f32x4*)(ldp + pt * 256);
;                 unsigned vsave = *(const LAS unsigned*)(lds + CK_STG + (it & 1) * CK_STG_SZ + 16384 + (pt * 16 + pj) * 4);
;                 asm volatile("" : "+v"(nkk), "+v"(be), "+v"(kp), "+v"(rf), "+v"(lf), "+v"(vsave));
;                 f32x4 Gc = (f32x4){0.f, 0.f, 0.f, 0.f};
;                 const int w4 = 4 * wq;
; #pragma unroll
;                 for (int s4 = 0; s4 < 16; s4 += 4) {
;                     if (s4 <= w4) {
;                         f32x4 x0 = *(const LAS f32x4*)(ldp + (s4 + 0) * 256), x1 = *(const LAS f32x4*)(ldp + (s4 + 1) * 256), x2 = *(const LAS f32x4*)(ldp + (s4 + 2) * 256), x3 = *(const LAS f32x4*)(ldp + (s4 + 3) * 256);
;                         asm volatile("" : "+v"(x0), "+v"(x1), "+v"(x2), "+v"(x3));
;                         if (s4 < w4) Gc += (x0 + x1) + (x2 + x3);
;                         else { const f32x4 z4 = (f32x4){0.f, 0.f, 0.f, 0.f};
;                             Gc += (s4 + 0 <= pt) ? x0 : z4; Gc += (s4 + 1 <= pt) ? x1 : z4; Gc += (s4 + 2 <= pt) ? x2 : z4; Gc += (s4 + 3 <= pt) ? x3 : z4; }
;                     }
;                 }
.Lmy_p1_noload:
	v_lshlrev_b32_e32 v2, 16, v134
	v_and_b32_e32 v3, 0xffff0000, v134
	v_lshlrev_b32_e32 v36, 16, v135
	v_and_b32_e32 v37, 0xffff0000, v135
	v_pk_mul_f32 v[44:45], v[8:9], v[2:3]
	v_pk_mul_f32 v[46:47], v[10:11], v[36:37]
	v_pk_mul_f32 v[48:49], v[44:45], v[44:45]
	v_pk_mul_f32 v[38:39], v[46:47], v[46:47]
	v_lshlrev_b32_e32 v40, 16, v140
	v_and_b32_e32 v41, 0xffff0000, v140
	v_lshlrev_b32_e32 v42, 16, v141
	v_and_b32_e32 v43, 0xffff0000, v141
	v_pk_mov_b32 v[50:51], v[48:49], v[38:39] op_sel:[1,0]
	v_mov_b32_e32 v49, v39
	s_andn2_b32 s0, 1, s62
	v_pk_add_f32 v[48:49], v[50:51], v[48:49]
	s_mul_i32 s1, s0, 0x4400
	v_pk_add_f32 v[38:39], v[42:43], -1.0 op_sel_hi:[1,0]
	v_pk_add_f32 v[50:51], v[40:41], -1.0 op_sel_hi:[1,0]
	s_add_i32 s1, s1, 0
	v_pk_fma_f32 v[50:51], v[4:5], v[50:51], 1.0 op_sel_hi:[1,1,0]
	v_pk_fma_f32 v[38:39], v[6:7], v[38:39], 1.0 op_sel_hi:[1,1,0]
	s_mulk_i32 s0, 0xcc00
	v_add_u32_e32 v1, s1, v99
	v_pk_mul_f32 v[38:39], v[38:39], v[36:37]
	v_pk_mul_f32 v[36:37], v[50:51], v[2:3]
	v_add_u32_e32 v2, s1, v103
	s_add_i32 s0, s1, s0
	v_lshlrev_b32_e32 v28, 16, v138
	v_and_b32_e32 v29, 0xffff0000, v138
	v_lshlrev_b32_e32 v30, 16, v139
	v_and_b32_e32 v31, 0xffff0000, v139
	v_lshlrev_b32_e32 v32, 16, v136
	v_and_b32_e32 v33, 0xffff0000, v136
	v_lshlrev_b32_e32 v34, 16, v137
	v_and_b32_e32 v35, 0xffff0000, v137
	ds_write_b128 v1, v[36:39] offset:53248
	ds_write_b128 v1, v[32:35] offset:57344
	ds_write_b32 v2, v187 offset:61440
	v_add_u32_e32 v2, s0, v99
	ds_write_b128 v2, v[28:31] offset:31744
	v_lshlrev_b32_e32 v2, 16, v126
	v_and_b32_e32 v3, 0xffff0000, v126
	v_lshlrev_b32_e32 v50, 16, v127
	v_and_b32_e32 v51, 0xffff0000, v127
	v_pk_mul_f32 v[56:57], v[8:9], v[2:3]
	v_pk_mul_f32 v[58:59], v[10:11], v[50:51]
	v_pk_mul_f32 v[36:37], v[56:57], v[56:57]
	v_pk_mul_f32 v[34:35], v[58:59], v[58:59]
	v_lshlrev_b32_e32 v52, 16, v132
	v_pk_mov_b32 v[38:39], v[36:37], v[34:35] op_sel:[1,0]
	v_mov_b32_e32 v37, v35
	v_pk_add_f32 v[34:35], v[38:39], v[36:37]
	v_mov_b32_e32 v37, v48
	v_mov_b32_e32 v36, v34
	v_mov_b32_e32 v48, v35
	v_pk_add_f32 v[34:35], v[36:37], v[48:49]
	v_and_b32_e32 v53, 0xffff0000, v132
	v_lshlrev_b32_e32 v54, 16, v133
	v_mov_b32_dpp v37, v35 quad_perm:[1,0,3,2] row_mask:0xf bank_mask:0xf bound_ctrl:1
	v_mov_b32_dpp v36, v34 quad_perm:[1,0,3,2] row_mask:0xf bank_mask:0xf bound_ctrl:1
	v_pk_add_f32 v[34:35], v[34:35], v[36:37]
	v_and_b32_e32 v55, 0xffff0000, v133
	v_lshlrev_b32_e32 v32, 16, v128
	v_mov_b32_dpp v37, v35 quad_perm:[2,3,0,1] row_mask:0xf bank_mask:0xf bound_ctrl:1
	v_mov_b32_dpp v36, v34 quad_perm:[2,3,0,1] row_mask:0xf bank_mask:0xf bound_ctrl:1
	v_pk_add_f32 v[34:35], v[34:35], v[36:37]
	v_and_b32_e32 v33, 0xffff0000, v128
	v_lshlrev_b32_e32 v28, 16, v130
	v_mov_b32_dpp v37, v35 row_half_mirror row_mask:0xf bank_mask:0xf bound_ctrl:1
	v_mov_b32_dpp v36, v34 row_half_mirror row_mask:0xf bank_mask:0xf bound_ctrl:1
	v_pk_add_f32 v[34:35], v[34:35], v[36:37]
	v_and_b32_e32 v29, 0xffff0000, v130
	v_lshlrev_b32_e32 v30, 16, v131
	v_mov_b32_dpp v37, v35 row_mirror row_mask:0xf bank_mask:0xf bound_ctrl:1
	v_mov_b32_dpp v36, v34 row_mirror row_mask:0xf bank_mask:0xf bound_ctrl:1
	v_pk_add_f32 v[48:49], v[34:35], v[36:37]
	v_lshlrev_b32_e32 v34, 16, v129
	v_rsq_f32_e32 v36, v49
	v_cmp_lt_f32_e32 vcc, s74, v49
	v_and_b32_e32 v35, 0xffff0000, v129
	v_and_b32_e32 v31, 0xffff0000, v131
	v_cndmask_b32_e32 v36, v183, v36, vcc
	v_pk_mul_f32 v[38:39], v[46:47], v[36:37] op_sel_hi:[1,0] neg_lo:[0,1] neg_hi:[0,1]
	v_pk_mul_f32 v[36:37], v[44:45], v[36:37] op_sel_hi:[1,0] neg_lo:[0,1] neg_hi:[0,1]
	ds_write_b128 v1, v[36:39] offset:45056
	v_pk_mul_f32 v[38:39], v[38:39], v[42:43] neg_lo:[1,0] neg_hi:[1,0]
	v_rsq_f32_e32 v42, v48
	v_pk_mul_f32 v[36:37], v[36:37], v[40:41] neg_lo:[1,0] neg_hi:[1,0]
	v_cmp_lt_f32_e32 vcc, s74, v48
	ds_write_b128 v1, v[36:39] offset:49152
	v_add_u32_e32 v1, s1, v105
	v_cndmask_b32_e32 v36, v183, v42, vcc
	v_pk_mul_f32 v[38:39], v[58:59], v[36:37] op_sel_hi:[1,0] neg_lo:[0,1] neg_hi:[0,1]
	v_pk_mul_f32 v[36:37], v[56:57], v[36:37] op_sel_hi:[1,0] neg_lo:[0,1] neg_hi:[0,1]
	ds_write_b128 v1, v[36:39] offset:45056
	v_pk_mul_f32 v[38:39], v[38:39], v[54:55] neg_lo:[1,0] neg_hi:[1,0]
	v_pk_mul_f32 v[36:37], v[36:37], v[52:53] neg_lo:[1,0] neg_hi:[1,0]
	ds_write_b128 v1, v[36:39] offset:49152
	v_pk_add_f32 v[36:37], v[54:55], -1.0 op_sel_hi:[1,0]
	v_pk_add_f32 v[38:39], v[52:53], -1.0 op_sel_hi:[1,0]
	v_pk_fma_f32 v[36:37], v[6:7], v[36:37], 1.0 op_sel_hi:[1,1,0]
	v_pk_fma_f32 v[40:41], v[4:5], v[38:39], 1.0 op_sel_hi:[1,1,0]
	v_pk_mul_f32 v[38:39], v[36:37], v[50:51]
	v_pk_mul_f32 v[36:37], v[40:41], v[2:3]
	ds_write_b128 v1, v[36:39] offset:53248
	ds_write_b128 v1, v[32:35] offset:57344
	v_add3_u32 v1, s1, v155, v102
	ds_write_b32 v1, v186 offset:61440
	v_add_u32_e32 v1, s0, v105
	ds_write_b128 v1, v[28:31] offset:31744
.LBB0_921:
	s_cmp_ge_u32 s60, 0x7f8000
	s_cselect_b64 s[0:1], -1, 0
	s_or_b64 s[0:1], s[58:59], s[0:1]
	s_and_b64 vcc, exec, s[0:1]
	s_cbranch_vccnz .LBB0_949
	s_and_b32 s78, s62, 1
	s_mul_i32 s0, s78, 0x4400
	s_add_i32 s96, s0, 0
	v_lshl_add_u32 v73, s78, 12, v160
	v_add3_u32 v3, s96, v162, v102
	v_add3_u32 v1, s96, v161, v104
	v_add_u32_e32 v2, v73, v161
	ds_read_b32 v72, v3 offset:61440
	ds_read_b128 v[44:47], v2 offset:31744
	ds_read_b128 v[36:39], v1 offset:57344
	ds_read_b128 v[28:31], v1 offset:53248
	ds_read_b128 v[32:35], v1 offset:49152
	ds_read_b128 v[40:43], v1 offset:45056
	s_and_b64 vcc, exec, s[52:53]
	s_waitcnt lgkmcnt(0)
	s_cbranch_vccnz .LBB0_925
	ds_read_b128 v[52:55], v73 offset:32512
	ds_read_b128 v[56:59], v73 offset:32256
	ds_read_b128 v[60:63], v73 offset:32000
	ds_read_b128 v[64:67], v73 offset:31744
	s_andn2_b64 vcc, exec, s[82:83]
	s_waitcnt lgkmcnt(0)
	s_cbranch_vccnz .LBB0_926
	v_pk_add_f32 v[2:3], v[66:67], v[62:63]
	v_pk_add_f32 v[48:49], v[64:65], v[60:61]
	v_pk_add_f32 v[50:51], v[58:59], v[54:55]
	v_pk_add_f32 v[68:69], v[56:57], v[52:53]
	v_pk_add_f32 v[2:3], v[2:3], v[50:51]
	v_pk_add_f32 v[48:49], v[48:49], v[68:69]
	v_pk_add_f32 v[50:51], v[2:3], 0 op_sel_hi:[1,0]
	v_pk_add_f32 v[48:49], v[48:49], 0 op_sel_hi:[1,0]
	s_cbranch_execz .LBB0_927
	s_branch .LBB0_928

; __device__ __forceinline__ void scan_phase(LAS unsigned char* lds, const bf16_t* R, const bf16_t* Kb, const bf16_t* V, const bf16_t* WA, const float* k_k, const float* k_a, bf16_t* Y, int G, int bid, int tid) {
;     ...
;                 f32x4 eA, eR, eN;
; #pragma unroll
;                 for (int e = 0; e < 4; ++e) { eA[e] = __expf(Gm[e]); eR[e] = __expf(Gc[e]); eN[e] = __expf(-Gc[e]); }
;                 const f32x4 ab = nkk * eA, rb = rf * eR, bt = be * eN, kt_ = kp * eN;
;                 const unsigned ab0 = ck_cvt(ab.x, ab.y), ab1 = ck_cvt(ab.z, ab.w), rb0 = ck_cvt(rb.x, rb.y), rb1 = ck_cvt(rb.z, rb.w);
;                 const unsigned bt0 = ck_cvt(bt.x, bt.y), bt1 = ck_cvt(bt.z, bt.w), kt0 = ck_cvt(kt_.x, kt_.y), kt1 = ck_cvt(kt_.z, kt_.w);
;                 LAS unsigned char* rowp = buf + pt * CK_RP + 64 * (pj >> 3) + 16 * (pj & 3) + 8 * ((pj >> 2) & 1);
;                 *(LAS u32x2*)(rowp + CK_ABAR) = (u32x2){ab0, ab1}; *(LAS u32x2*)(rowp + CK_RBAR) = (u32x2){rb0, rb1};
;                 *(LAS u32x2*)(rowp + CK_BTIL) = (u32x2){bt0, bt1}; *(LAS u32x2*)(rowp + CK_KTIL) = (u32x2){kt0, kt1};
;                 constexpr int TS = CK_TP / 2;
;                 {
;                     const int rrow = lane >> 4;
;     ...
;                     unsigned b0_ = __float_as_uint(bt.x), b1_ = __float_as_uint(bt.y), b2_ = __float_as_uint(bt.z), b3_ = __float_as_uint(bt.w);
;                     unsigned k0_ = __float_as_uint(kt_.x), k1_ = __float_as_uint(kt_.y), k2_ = __float_as_uint(kt_.z), k3_ = __float_as_uint(kt_.w);
;                     CK_T4(b0_, b1_, b2_, b3_); CK_T4(k0_, k1_, k2_, k3_);
;     ...
;                     const int toff = (4 * pj + rrow) * CK_TP + 8 * wq;
;                     *(LAS u32x2*)(buf + CK_BT_T + toff) = (u32x2){ck_cvt(__uint_as_float(b0_), __uint_as_float(b1_)), ck_cvt(__uint_as_float(b2_), __uint_as_float(b3_))};
;                     *(LAS u32x2*)(buf + CK_KT_T + toff) = (u32x2){ck_cvt(__uint_as_float(k0_), __uint_as_float(k1_)), ck_cvt(__uint_as_float(k2_), __uint_as_float(k3_))};
;                 }
;                 LAS unsigned short* vT = (LAS unsigned short*)(buf + CK_VT + (2 * pj) * CK_TP + pt * 2);
;                 vT[0] = (unsigned short)(vsave & 0xffffu); vT[TS] = (unsigned short)(vsave >> 16);
;                 if (pt == 15) *(LAS f32x4*)(buf + CK_GAM + 16 * pj) = eR;
;             }
;             if (consumer && it > 0) {
.LBB0_946:
	v_sub_f32_e32 v1, v51, v47
	v_sub_f32_e32 v46, v50, v46
	v_sub_f32_e32 v3, v49, v45
	v_mul_f32_e32 v45, 0xbfb8aa3b, v48
	v_mul_f32_e32 v47, 0xbfb8aa3b, v49
	v_mul_f32_e32 v1, 0x3fb8aa3b, v1
	v_sub_f32_e32 v2, v48, v44
	v_mul_f32_e32 v44, 0x3fb8aa3b, v48
	v_exp_f32_e32 v48, v45
	v_mul_f32_e32 v45, 0x3fb8aa3b, v49
	v_exp_f32_e32 v49, v47
	v_mul_f32_e32 v46, 0x3fb8aa3b, v46
	v_mul_f32_e32 v47, 0xbfb8aa3b, v50
	v_exp_f32_e32 v53, v1
	v_mul_f32_e32 v1, 0x3fb8aa3b, v51
	v_mul_f32_e32 v2, 0x3fb8aa3b, v2
	v_mul_f32_e32 v3, 0x3fb8aa3b, v3
	v_exp_f32_e32 v52, v46
	v_mul_f32_e32 v46, 0x3fb8aa3b, v50
	v_exp_f32_e32 v50, v47
	v_exp_f32_e32 v47, v1
	v_mul_f32_e32 v1, 0xbfb8aa3b, v51
	v_exp_f32_e32 v2, v2
	v_exp_f32_e32 v44, v44
	v_exp_f32_e32 v3, v3
	v_exp_f32_e32 v45, v45
	v_exp_f32_e32 v46, v46
	v_exp_f32_e32 v51, v1
	s_and_b32 s96, s62, 3
	s_mul_i32 s96, s96, 0x3e00
	s_add_i32 s96, s96, 0x14000
	v_pk_mul_f32 v[42:43], v[42:43], v[52:53]
	v_pk_mul_f32 v[2:3], v[40:41], v[2:3]
	v_pk_mul_f32 v[38:39], v[38:39], v[46:47]
	v_pk_mul_f32 v[36:37], v[36:37], v[44:45]
	v_pk_mul_f32 v[34:35], v[34:35], v[50:51]
	v_pk_mul_f32 v[32:33], v[32:33], v[48:49]
	v_add3_u32 v1, s96, v163, v164
	v_pk_mul_f32 v[30:31], v[30:31], v[50:51]
	v_pk_mul_f32 v[28:29], v[28:29], v[48:49]
	v_cvt_pk_bf16_f32 v2, v2, v3
	v_cvt_pk_bf16_f32 v3, v42, v43
	v_cvt_pk_bf16_f32 v36, v36, v37
	v_cvt_pk_bf16_f32 v37, v38, v39
	v_cvt_pk_bf16_f32 v38, v32, v33
	v_cvt_pk_bf16_f32 v39, v34, v35
	v_add3_u32 v1, v1, v165, v166
	v_permlane32_swap_b32_e32 v33, v35
	v_cvt_pk_bf16_f32 v40, v28, v29
	v_cvt_pk_bf16_f32 v41, v30, v31
	ds_write_b64 v1, v[2:3]
	ds_write_b64 v1, v[36:37] offset:2304
	ds_write_b64 v1, v[38:39] offset:4608
	ds_write_b64 v1, v[40:41] offset:6912
	v_permlane32_swap_b32_e32 v32, v34
	v_mov_b32_e32 v1, v33
	v_mov_b32_e32 v3, v35
	v_permlane32_swap_b32_e32 v28, v30
	v_permlane32_swap_b32_e32 v29, v31
	v_permlane16_swap_b32_e32 v32, v1
	v_permlane16_swap_b32_e32 v34, v3
	v_permlane16_swap_b32_e32 v28, v29
	v_permlane16_swap_b32_e32 v30, v31
	v_cvt_pk_bf16_f32 v2, v32, v1
	v_cvt_pk_bf16_f32 v3, v34, v3
	v_add_u32_e32 v1, s96, v167
	v_cvt_pk_bf16_f32 v28, v28, v29
	v_cvt_pk_bf16_f32 v29, v30, v31
	ds_write2st64_b64 v1, v[2:3], v[28:29] offset0:18 offset1:23
	v_add3_u32 v1, s96, v168, v169
	ds_write_b16 v1, v72 offset:14336
	ds_write_b16_d16_hi v1, v72 offset:14376
	s_and_saveexec_b64 s[0:1], s[2:3]
	v_add_u32_e32 v1, s96, v104
	ds_write_b128 v1, v[44:47] offset:15616
	s_or_b64 exec, exec, s[0:1]
.LBB0_949:
	s_andn2_b64 vcc, exec, s[76:77]
	s_cbranch_vccnz .LBB0_915
	s_cmp_lg_u32 s33, 0
	s_cbranch_scc1 .Lmy_helper
	s_cmp_lt_u32 s62, 2
	s_cbranch_scc1 .LBB0_915
	s_cmp_lg_u32 s62, 2
	s_cbranch_scc1 .Lmy_cons_body
	v_mbcnt_lo_u32_b32 v1, -1, 0
	v_mbcnt_hi_u32_b32 v1, -1, v1
	v_and_b32_e32 v2, 15, v1
	v_lshrrev_b32_e32 v3, 4, v1
	v_and_b32_e32 v96, 3, v2
	v_lshrrev_b32_e32 v97, 2, v2
	v_lshl_add_u32 v96, v96, 2, v97
	v_mul_u32_u24_e32 v170, 0x90, v96
	v_lshl_add_u32 v170, v3, 4, v170
	v_mul_u32_u24_e32 v171, 0x90, v2
	v_lshl_add_u32 v171, v3, 4, v171
	v_lshlrev_b32_e32 v97, 5, v96
	v_lshl_add_u32 v172, v3, 3, v97
	v_lshlrev_b32_e32 v173, 4, v1
	v_lshlrev_b32_e32 v174, 2, v1
	v_mul_u32_u24_e32 v175, 40, v2
	v_lshl_add_u32 v175, v3, 3, v175
	v_lshlrev_b32_e32 v188, 4, v3
	s_mov_b32 s0, 0x3ff8000
	s_mov_b32 s1, 0
	v_lshl_add_u64 v[190:191], v[142:143], 0, s[0:1]
	s_mov_b32 s0, 0x3ff9000
	v_lshl_add_u64 v[192:193], v[142:143], 0, s[0:1]
	v_mov_b32_e32 v12, 0
	v_mov_b32_e32 v13, 0
	v_mov_b32_e32 v14, 0
	v_mov_b32_e32 v15, 0
	v_mov_b32_e32 v16, 0
	v_mov_b32_e32 v17, 0
	v_mov_b32_e32 v18, 0
	v_mov_b32_e32 v19, 0
	v_mov_b32_e32 v20, 0
	v_mov_b32_e32 v21, 0
	v_mov_b32_e32 v22, 0
	v_mov_b32_e32 v23, 0
	v_mov_b32_e32 v24, 0
	v_mov_b32_e32 v25, 0
	v_mov_b32_e32 v26, 0
	v_mov_b32_e32 v27, 0
	v_mov_b32_e32 v28, 0
	v_mov_b32_e32 v29, 0
	v_mov_b32_e32 v30, 0
	v_mov_b32_e32 v31, 0
	v_mov_b32_e32 v32, 0
	v_mov_b32_e32 v33, 0
	v_mov_b32_e32 v34, 0
	v_mov_b32_e32 v35, 0
	v_mov_b32_e32 v36, 0
	v_mov_b32_e32 v37, 0
	v_mov_b32_e32 v38, 0
	v_mov_b32_e32 v39, 0
	v_mov_b32_e32 v40, 0
	v_mov_b32_e32 v41, 0
	v_mov_b32_e32 v42, 0
	v_mov_b32_e32 v43, 0
	v_mov_b32_e32 v46, 0
	v_mov_b32_e32 v47, 0
	v_mov_b32_e32 v50, 0
	v_mov_b32_e32 v51, 0
	v_mov_b32_e32 v54, 0
	v_mov_b32_e32 v55, 0
	v_mov_b32_e32 v58, 0
	v_mov_b32_e32 v59, 0
	v_mov_b32_e32 v78, 0
	v_mov_b32_e32 v79, 0
	v_mov_b32_e32 v84, 0
	v_mov_b32_e32 v85, 0
	v_mov_b32_e32 v62, 0
	v_mov_b32_e32 v63, 0
	v_mov_b32_e32 v66, 0
	v_mov_b32_e32 v67, 0
	v_mov_b32_e32 v70, 0
	v_mov_b32_e32 v71, 0
	v_mov_b32_e32 v74, 0
	v_mov_b32_e32 v75, 0
; __device__ __forceinline__ void scan_phase(LAS unsigned char* lds, const bf16_t* R, const bf16_t* Kb, const bf16_t* V, const bf16_t* WA, const float* k_k, const float* k_a, bf16_t* Y, int G, int bid, int tid) {
;     ...
;             if (consumer && it > 0) {
;                 const int cn = it - 1;
;                 const LAS unsigned char* buf = lds + (cn & 1) * CK_BUF;
;                 LAS unsigned char* priv = lds + CK_PRIV + wave * CK_PRIV_SZ;
;                 LAS float* AabT = (LAS float*)priv; LAS float* Xch = (LAS float*)(priv + 1024); LAS unsigned char* UT = priv + 2048;
;                 f32x4 xab = (f32x4){0.f, 0.f, 0.f, 0.f}, xak = xab, xrb = xab, xrk = xab;
;                 bf16x8 pa[2], pr[2];
; #pragma unroll
;                 for (int ks = 0; ks < 2; ++ks) {
;                     const LAS unsigned char* rp = buf + c * CK_RP + 64 * ks + 16 * g;
;                     pa[ks] = *(const LAS bf16x8*)(rp + CK_ABAR); pr[ks] = *(const LAS bf16x8*)(rp + CK_RBAR);
;                     const bf16x8 pb = *(const LAS bf16x8*)(rp + CK_BTIL), pk = *(const LAS bf16x8*)(rp + CK_KTIL);
;                     xab = CK_MFMA(pb, pa[ks], xab); xak = CK_MFMA(pk, pa[ks], xak); xrb = CK_MFMA(pb, pr[ks], xrb); xrk = CK_MFMA(pk, pr[ks], xrk);
;                 }
; #pragma unroll
;                 for (int r = 0; r < 4; ++r) { const int s = 4 * g + r; if (!(s < c)) { xab[r] = 0.f; xak[r] = 0.f; } if (!(s <= c)) { xrb[r] = 0.f; xrk[r] = 0.f; } }
; #pragma unroll
;                 for (int r = 0; r < 4; ++r) AabT[(4 * g + r) * 16 + c] = xab[r];
;                 const bf16x8 opak = ck_pk4(xak), oprb = ck_pk4(xrb), oprk = ck_pk4(xrk);
;                 bf16x8 oph[2];
; #pragma unroll
;                 for (int ks = 0; ks < 2; ++ks) oph[ks] = __builtin_bit_cast(bf16x8, (u32x4){ck_cvt(H[2 * ks][0], H[2 * ks][1]), ck_cvt(H[2 * ks][2], H[2 * ks][3]), ck_cvt(H[2 * ks + 1][0], H[2 * ks + 1][1]), ck_cvt(H[2 * ks + 1][2], H[2 * ks + 1][3])});
;                 const bf16x8 opv = ck_ld1(buf + CK_VT + (wave * 16 + c) * CK_TP + g * 8);
;                 f32x4 rhs = (f32x4){0.f, 0.f, 0.f, 0.f};
;                 rhs = CK_MFMA(pa[0], oph[0], rhs); rhs = CK_MFMA(pa[1], oph[1], rhs); rhs = CK_MFMA(opak, opv, rhs);
;                 float u[16];
; #pragma unroll
;                 for (int r = 0; r < 4; ++r) {
;                     const unsigned a_ = __float_as_uint(rhs[r]);
.Lmy_cons_body:
	s_add_i32 s0, s63, -1
	s_and_b32 s1, s0, 1
	s_lshl_b32 s1, s1, 12
	s_and_b32 s0, s0, 3
	s_mul_i32 s0, s0, 0x3e00
	s_add_i32 s0, s0, 0x14000
	v_add_u32_e32 v198, s0, v175
	v_add_u32_e32 v195, s1, v172
	v_add_u32_e32 v189, s0, v170
	v_add_u32_e32 v194, s0, v171
	v_add_u32_e32 v196, s1, v173
	v_add_u32_e32 v197, s1, v174
	v_add_u32_e32 v199, s0, v188
	ds_read_b64 v[44:45], v198 offset:14336
	ds_read_b64 v[48:49], v198 offset:14976
	ds_read_b64 v[76:77], v195 offset:1024
	ds_read_b128 v[88:91], v189
	ds_read_b128 v[92:95], v189 offset:64
	ds_read_b128 v[204:207], v194 offset:2304
	ds_read_b128 v[208:211], v194 offset:2368
	ds_read_b128 v[80:83], v196 offset:2048
	ds_read_b32 v212, v197 offset:0
	ds_read_b32 v213, v197 offset:256
	ds_read_b32 v214, v197 offset:512
	ds_read_b32 v215, v197 offset:768
	v_lshl_add_u64 v[200:201], v[190:191], 0, s[60:61]
	v_lshl_add_u64 v[202:203], v[192:193], 0, s[60:61]
	v_cvt_pk_bf16_f32 v216, v12, v13
	v_cvt_pk_bf16_f32 v217, v14, v15
	v_cvt_pk_bf16_f32 v218, v16, v17
	v_cvt_pk_bf16_f32 v219, v18, v19
	v_cvt_pk_bf16_f32 v220, v20, v21
	v_cvt_pk_bf16_f32 v221, v22, v23
	v_cvt_pk_bf16_f32 v222, v24, v25
	v_cvt_pk_bf16_f32 v223, v26, v27
	v_cvt_pk_bf16_f32 v224, v28, v29
	v_cvt_pk_bf16_f32 v225, v30, v31
	v_cvt_pk_bf16_f32 v226, v32, v33
	v_cvt_pk_bf16_f32 v227, v34, v35
	v_cvt_pk_bf16_f32 v228, v36, v37
	v_cvt_pk_bf16_f32 v229, v38, v39
	v_cvt_pk_bf16_f32 v230, v40, v41
	v_cvt_pk_bf16_f32 v231, v42, v43
	s_waitcnt lgkmcnt(9)
	v_mfma_f32_16x16x32_bf16 v[232:235], v[76:79], v[44:47], 0
	v_mfma_f32_16x16x32_bf16 v[236:239], v[76:79], v[48:51], 0
	ds_read_b64 v[60:61], v198 offset:11776
	ds_read_b64 v[64:65], v198 offset:12416
	ds_read_b64 v[68:69], v198 offset:13056
	ds_read_b64 v[72:73], v198 offset:13696
	s_waitcnt lgkmcnt(11)
	v_mfma_f32_16x16x32_bf16 v[232:235], v[88:91], v[216:219], v[232:235]
	v_mfma_f32_16x16x32_bf16 v[236:239], v[88:91], v[224:227], v[236:239]
	v_mfma_f32_16x16x32_bf16 v[232:235], v[92:95], v[220:223], v[232:235]
	v_mfma_f32_16x16x32_bf16 v[236:239], v[92:95], v[228:231], v[236:239]
	s_waitcnt lgkmcnt(8)
	v_mfma_f32_16x16x32_bf16 v[248:251], v[204:207], v[216:219], 0
	v_mfma_f32_16x16x32_bf16 v[156:159], v[204:207], v[224:227], 0
	v_mfma_f32_16x16x32_bf16 v[248:251], v[208:211], v[220:223], v[248:251]
	v_mfma_f32_16x16x32_bf16 v[156:159], v[208:211], v[228:231], v[156:159]
	v_mfma_f32_16x16x32_bf16 v[248:251], v[82:85], v[44:47], v[248:251]
	v_mfma_f32_16x16x32_bf16 v[156:159], v[82:85], v[48:51], v[156:159]
	s_waitcnt lgkmcnt(0)
	v_mfma_f32_16x16x32_bf16 v[12:15], v[60:63], v[44:47], v[12:15]
	v_mfma_f32_16x16x32_bf16 v[16:19], v[64:67], v[44:47], v[16:19]
	v_mfma_f32_16x16x32_bf16 v[20:23], v[68:71], v[44:47], v[20:23]
	v_mfma_f32_16x16x32_bf16 v[24:27], v[72:75], v[44:47], v[24:27]
	v_mfma_f32_16x16x32_bf16 v[28:31], v[60:63], v[48:51], v[28:31]
	v_mfma_f32_16x16x32_bf16 v[32:35], v[64:67], v[48:51], v[32:35]
	v_mfma_f32_16x16x32_bf16 v[36:39], v[68:71], v[48:51], v[36:39]
	v_mfma_f32_16x16x32_bf16 v[40:43], v[72:75], v[48:51], v[40:43]
	v_mfma_f32_16x16x4_f32 v[240:243], v212, v232, 0
	v_mfma_f32_16x16x4_f32 v[244:247], v212, v236, 0
	v_mfma_f32_16x16x4_f32 v[240:243], v213, v233, v[240:243]
	v_mfma_f32_16x16x4_f32 v[244:247], v213, v237, v[244:247]
	v_mfma_f32_16x16x4_f32 v[240:243], v214, v234, v[240:243]
	v_mfma_f32_16x16x4_f32 v[244:247], v214, v238, v[244:247]
	v_mfma_f32_16x16x4_f32 v[240:243], v215, v235, v[240:243]
	v_mfma_f32_16x16x4_f32 v[244:247], v215, v239, v[244:247]
	ds_read_b64 v[60:61], v198 offset:9216
	ds_read_b64 v[64:65], v198 offset:9856
	ds_read_b64 v[68:69], v198 offset:10496
	ds_read_b64 v[72:73], v198 offset:11136
	ds_read_b128 v[88:91], v199 offset:15616
	ds_read_b128 v[92:95], v199 offset:15680
	ds_read_b128 v[204:207], v199 offset:15744
	ds_read_b128 v[208:211], v199 offset:15808
	s_nop 4
	v_cvt_pk_bf16_f32 v52, v240, v241
	v_cvt_pk_bf16_f32 v53, v242, v243
	v_cvt_pk_bf16_f32 v56, v244, v245
	v_cvt_pk_bf16_f32 v57, v246, v247
	s_nop 1
	v_mfma_f32_16x16x32_bf16 v[248:251], v[80:83], v[52:55], v[248:251]
	v_mfma_f32_16x16x32_bf16 v[156:159], v[80:83], v[56:59], v[156:159]
	s_waitcnt lgkmcnt(4)
	v_mfma_f32_16x16x32_bf16 v[12:15], v[60:63], v[52:55], v[12:15]
	v_mfma_f32_16x16x32_bf16 v[16:19], v[64:67], v[52:55], v[16:19]
	v_mfma_f32_16x16x32_bf16 v[20:23], v[68:71], v[52:55], v[20:23]
	v_mfma_f32_16x16x32_bf16 v[24:27], v[72:75], v[52:55], v[24:27]
	v_mfma_f32_16x16x32_bf16 v[28:31], v[60:63], v[56:59], v[28:31]
	v_mfma_f32_16x16x32_bf16 v[32:35], v[64:67], v[56:59], v[32:35]
	v_mfma_f32_16x16x32_bf16 v[36:39], v[68:71], v[56:59], v[36:39]
	v_mfma_f32_16x16x32_bf16 v[40:43], v[72:75], v[56:59], v[40:43]
	v_cvt_pk_bf16_f32 v252, v248, v248
	global_store_short v[200:201], v252, off
	v_cvt_pk_bf16_f32 v252, v249, v249
	global_store_short v[200:201], v252, off offset:2048
	v_cvt_pk_bf16_f32 v252, v250, v250
	global_store_short v[202:203], v252, off
	v_cvt_pk_bf16_f32 v252, v251, v251
	global_store_short v[202:203], v252, off offset:2048
	v_cvt_pk_bf16_f32 v252, v156, v156
	global_store_short v[200:201], v252, off offset:32
	v_cvt_pk_bf16_f32 v252, v157, v157
	global_store_short v[200:201], v252, off offset:2080
	v_cvt_pk_bf16_f32 v252, v158, v158
	global_store_short v[202:203], v252, off offset:32
	v_cvt_pk_bf16_f32 v252, v159, v159
	global_store_short v[202:203], v252, off offset:2080
	s_waitcnt lgkmcnt(0)
	v_pk_mul_f32 v[12:13], v[12:13], v[88:89]
	v_pk_mul_f32 v[14:15], v[14:15], v[90:91]
	v_pk_mul_f32 v[16:17], v[16:17], v[92:93]
	v_pk_mul_f32 v[18:19], v[18:19], v[94:95]
	v_pk_mul_f32 v[20:21], v[20:21], v[204:205]
	v_pk_mul_f32 v[22:23], v[22:23], v[206:207]
	v_pk_mul_f32 v[24:25], v[24:25], v[208:209]
	v_pk_mul_f32 v[26:27], v[26:27], v[210:211]
	v_pk_mul_f32 v[28:29], v[28:29], v[88:89]
	v_pk_mul_f32 v[30:31], v[30:31], v[90:91]
	v_pk_mul_f32 v[32:33], v[32:33], v[92:93]
	v_pk_mul_f32 v[34:35], v[34:35], v[94:95]
	v_pk_mul_f32 v[36:37], v[36:37], v[204:205]
	v_pk_mul_f32 v[38:39], v[38:39], v[206:207]
	v_pk_mul_f32 v[40:41], v[40:41], v[208:209]
	v_pk_mul_f32 v[42:43], v[42:43], v[210:211]
	s_branch .LBB0_915
; #define LAS __attribute__((address_space(3)))
; __device__ __forceinline__ void scan_phase(LAS unsigned char* lds, const bf16_t* R, const bf16_t* Kb, const bf16_t* V, const bf16_t* WA, const float* k_k, const float* k_a, bf16_t* Y, int G, int bid, int tid) {
;     ...
;                 f32x4 xab = (f32x4){0.f, 0.f, 0.f, 0.f}, xak = xab, xrb = xab, xrk = xab;
;                 bf16x8 pa[2], pr[2];
; #pragma unroll
;                 for (int ks = 0; ks < 2; ++ks) {
;                     const LAS unsigned char* rp = buf + c * CK_RP + 64 * ks + 16 * g;
;                     pa[ks] = *(const LAS bf16x8*)(rp + CK_ABAR); pr[ks] = *(const LAS bf16x8*)(rp + CK_RBAR);
;                     const bf16x8 pb = *(const LAS bf16x8*)(rp + CK_BTIL), pk = *(const LAS bf16x8*)(rp + CK_KTIL);
;                     xab = CK_MFMA(pb, pa[ks], xab); xak = CK_MFMA(pk, pa[ks], xak); xrb = CK_MFMA(pb, pr[ks], xrb); xrk = CK_MFMA(pk, pr[ks], xrk);
;                 }
; #pragma unroll
;                 for (int r = 0; r < 4; ++r) { const int s = 4 * g + r; if (!(s < c)) { xab[r] = 0.f; xak[r] = 0.f; } if (!(s <= c)) { xrb[r] = 0.f; xrk[r] = 0.f; } }
; #pragma unroll
;                 for (int r = 0; r < 4; ++r) AabT[(4 * g + r) * 16 + c] = xab[r];
;                 const bf16x8 opak = ck_pk4(xak), oprb = ck_pk4(xrb), oprk = ck_pk4(xrk);
;                 bf16x8 oph[2];
; #pragma unroll
;                 for (int ks = 0; ks < 2; ++ks) oph[ks] = __builtin_bit_cast(bf16x8, (u32x4){ck_cvt(H[2 * ks][0], H[2 * ks][1]), ck_cvt(H[2 * ks][2], H[2 * ks][3]), ck_cvt(H[2 * ks + 1][0], H[2 * ks + 1][1]), ck_cvt(H[2 * ks + 1][2], H[2 * ks + 1][3])});
;                 const bf16x8 opv = ck_ld1(buf + CK_VT + (wave * 16 + c) * CK_TP + g * 8);
;                 f32x4 rhs = (f32x4){0.f, 0.f, 0.f, 0.f};
;                 rhs = CK_MFMA(pa[0], oph[0], rhs); rhs = CK_MFMA(pa[1], oph[1], rhs); rhs = CK_MFMA(opak, opv, rhs);
;                 float u[16];
; #pragma unroll
;                 for (int r = 0; r < 4; ++r) {
;                     const unsigned a_ = __float_as_uint(rhs[r]);
;                     const auto h_ = __builtin_amdgcn_permlane32_swap(a_, a_, false, false);
;                     const auto lo_ = __builtin_amdgcn_permlane16_swap(h_[0], h_[0], false, false);
;                     const auto hi_ = __builtin_amdgcn_permlane16_swap(h_[1], h_[1], false, false);
.Lmy_helper:
	s_cmp_gt_u32 s62, 0x100
	s_cbranch_scc1 .LBB0_915
	s_cmp_lg_u32 s62, 1
	s_cbranch_scc1 .Lmy_help_body
	v_mbcnt_lo_u32_b32 v1, -1, 0
	v_mbcnt_hi_u32_b32 v1, -1, v1
	v_and_b32_e32 v2, 15, v1
	v_lshrrev_b32_e32 v3, 4, v1
	v_mul_u32_u24_e32 v170, 0x90, v2
	v_lshl_add_u32 v170, v3, 4, v170
	v_lshlrev_b32_e32 v171, 4, v1
	v_lshlrev_b32_e32 v96, 5, v2
	v_lshl_add_u32 v172, v3, 3, v96
	v_lshlrev_b32_e32 v96, 8, v3
	v_lshl_add_u32 v173, v2, 2, v96
	v_add_u32_e32 v173, 0x2000, v173
	v_lshlrev_b32_e32 v174, 6, v2
	v_lshl_add_u32 v174, v3, 4, v174
	v_mov_b32_e32 v175, 0x2000
	v_lshlrev_b32_e32 v97, 2, v3
	v_add_u32_e32 v96, 0, v97
	v_cmp_lt_u32_e32 vcc, v96, v2
	s_nop 1
	v_cndmask_b32_e64 v188, 0, -1, vcc
	v_cmp_le_u32_e32 vcc, v96, v2
	s_nop 1
	v_cndmask_b32_e64 v192, 0, -1, vcc
	v_add_u32_e32 v96, 1, v97
	v_cmp_lt_u32_e32 vcc, v96, v2
	s_nop 1
	v_cndmask_b32_e64 v189, 0, -1, vcc
	v_cmp_le_u32_e32 vcc, v96, v2
	s_nop 1
	v_cndmask_b32_e64 v193, 0, -1, vcc
	v_add_u32_e32 v96, 2, v97
	v_cmp_lt_u32_e32 vcc, v96, v2
	s_nop 1
	v_cndmask_b32_e64 v190, 0, -1, vcc
	v_cmp_le_u32_e32 vcc, v96, v2
	s_nop 1
	v_cndmask_b32_e64 v194, 0, -1, vcc
	v_add_u32_e32 v96, 3, v97
	v_cmp_lt_u32_e32 vcc, v96, v2
	s_nop 1
	v_cndmask_b32_e64 v191, 0, -1, vcc
	v_cmp_le_u32_e32 vcc, v96, v2
	s_nop 1
	v_cndmask_b32_e64 v195, 0, -1, vcc
	v_cmp_eq_u32_e32 vcc, 0, v2
	s_nop 1
	v_cndmask_b32_e64 v196, 0, 1.0, vcc
	v_cmp_eq_u32_e32 vcc, 1, v2
	s_nop 1
	v_cndmask_b32_e64 v197, 0, 1.0, vcc
	v_cmp_eq_u32_e32 vcc, 2, v2
	s_nop 1
	v_cndmask_b32_e64 v198, 0, 1.0, vcc
	v_cmp_eq_u32_e32 vcc, 3, v2
	s_nop 1
	v_cndmask_b32_e64 v199, 0, 1.0, vcc
	v_cmp_eq_u32_e32 vcc, 4, v2
	s_nop 1
	v_cndmask_b32_e64 v200, 0, 1.0, vcc
	v_cmp_eq_u32_e32 vcc, 5, v2
	s_nop 1
	v_cndmask_b32_e64 v201, 0, 1.0, vcc
	v_cmp_eq_u32_e32 vcc, 6, v2
	s_nop 1
	v_cndmask_b32_e64 v202, 0, 1.0, vcc
	v_cmp_eq_u32_e32 vcc, 7, v2
	s_nop 1
	v_cndmask_b32_e64 v203, 0, 1.0, vcc
	v_cmp_eq_u32_e32 vcc, 8, v2
	s_nop 1
	v_cndmask_b32_e64 v204, 0, 1.0, vcc
	v_cmp_eq_u32_e32 vcc, 9, v2
	s_nop 1
	v_cndmask_b32_e64 v205, 0, 1.0, vcc
	v_cmp_eq_u32_e32 vcc, 10, v2
	s_nop 1
	v_cndmask_b32_e64 v206, 0, 1.0, vcc
	v_cmp_eq_u32_e32 vcc, 11, v2
	s_nop 1
	v_cndmask_b32_e64 v207, 0, 1.0, vcc
	v_cmp_eq_u32_e32 vcc, 12, v2
	s_nop 1
	v_cndmask_b32_e64 v208, 0, 1.0, vcc
	v_cmp_eq_u32_e32 vcc, 13, v2
	s_nop 1
	v_cndmask_b32_e64 v209, 0, 1.0, vcc
	v_cmp_eq_u32_e32 vcc, 14, v2
	s_nop 1
	v_cndmask_b32_e64 v210, 0, 1.0, vcc
	v_cmp_eq_u32_e32 vcc, 15, v2
	s_nop 1
	v_cndmask_b32_e64 v211, 0, 1.0, vcc
.Lmy_help_body:
	s_and_b32 s1, s63, 1
	s_lshl_b32 s1, s1, 12
	s_and_b32 s0, s63, 3
	s_mul_i32 s0, s0, 0x3e00
	s_add_i32 s0, s0, 0x14000
	v_add_u32_e32 v88, s0, v170
	v_add_u32_e32 v89, s1, v171
	v_add_u32_e32 v90, s1, v172
	v_add_u32_e32 v91, s1, v174
	ds_read_b128 v[12:15], v88 offset:4608
	ds_read_b128 v[28:31], v88 offset:0
	ds_read_b128 v[16:19], v88 offset:4672
	ds_read_b128 v[32:35], v88 offset:64
	ds_read_b128 v[20:23], v88 offset:6912
	ds_read_b128 v[24:27], v88 offset:6976
	ds_read_b128 v[36:39], v88 offset:2304
	ds_read_b128 v[40:43], v88 offset:2368
	s_waitcnt lgkmcnt(6)
	v_mfma_f32_16x16x32_bf16 v[232:235], v[12:15], v[28:31], 0
	s_waitcnt lgkmcnt(4)
	v_mfma_f32_16x16x32_bf16 v[232:235], v[16:19], v[32:35], v[232:235]
	s_waitcnt lgkmcnt(2)
	v_mfma_f32_16x16x32_bf16 v[236:239], v[20:23], v[28:31], 0
	v_mfma_f32_16x16x32_bf16 v[236:239], v[24:27], v[32:35], v[236:239]
	s_waitcnt lgkmcnt(0)
	v_mfma_f32_16x16x32_bf16 v[240:243], v[12:15], v[36:39], 0
	v_mfma_f32_16x16x32_bf16 v[244:247], v[20:23], v[36:39], 0
	v_mfma_f32_16x16x32_bf16 v[240:243], v[16:19], v[40:43], v[240:243]
	v_mfma_f32_16x16x32_bf16 v[244:247], v[24:27], v[40:43], v[244:247]
	v_mov_b64_e32 v[216:217], v[196:197]
	v_mov_b64_e32 v[218:219], v[198:199]
	v_mov_b64_e32 v[220:221], v[200:201]
	v_mov_b64_e32 v[222:223], v[202:203]
	v_mov_b64_e32 v[224:225], v[204:205]
	v_mov_b64_e32 v[226:227], v[206:207]
	v_mov_b64_e32 v[228:229], v[208:209]
	v_mov_b64_e32 v[230:231], v[210:211]
	v_and_b32_e32 v232, v232, v188
	v_and_b32_e32 v233, v233, v189
	v_and_b32_e32 v234, v234, v190
	v_and_b32_e32 v235, v235, v191
	ds_write2_b32 v173, v232, v233 offset1:16
	ds_write2_b32 v173, v234, v235 offset0:32 offset1:48
	ds_read_b128 v[12:15], v175 offset:0
	ds_read_b128 v[16:19], v175 offset:16
	ds_read_b128 v[20:23], v175 offset:32
	ds_read_b128 v[24:27], v175 offset:48
	ds_read_b128 v[28:31], v175 offset:64
	ds_read_b128 v[32:35], v175 offset:80
	ds_read_b128 v[36:39], v175 offset:96
	ds_read_b128 v[40:43], v175 offset:112
	ds_read_b128 v[44:47], v175 offset:128
	ds_read_b128 v[48:51], v175 offset:144
	ds_read_b128 v[52:55], v175 offset:160
	ds_read_b128 v[56:59], v175 offset:176
	v_and_b32_e32 v236, v236, v188
	v_and_b32_e32 v237, v237, v189
	v_and_b32_e32 v238, v238, v190
	v_and_b32_e32 v239, v239, v191
	v_cvt_pk_bf16_f32 v76, v236, v237
	v_cvt_pk_bf16_f32 v77, v238, v239
	v_and_b32_e32 v240, v240, v192
	v_and_b32_e32 v241, v241, v193
	v_and_b32_e32 v242, v242, v194
	v_and_b32_e32 v243, v243, v195
	v_cvt_pk_bf16_f32 v80, v240, v241
	v_cvt_pk_bf16_f32 v81, v242, v243
	v_and_b32_e32 v244, v244, v192
	v_and_b32_e32 v245, v245, v193
	v_and_b32_e32 v246, v246, v194
	v_and_b32_e32 v247, v247, v195
	v_cvt_pk_bf16_f32 v82, v244, v245
	v_cvt_pk_bf16_f32 v83, v246, v247
	s_waitcnt lgkmcnt(8)
	ds_write_b64 v90, v[76:77] offset:1024
	ds_write_b128 v89, v[80:83] offset:2048
	ds_read_b128 v[60:63], v175 offset:208
	ds_read_b128 v[64:67], v175 offset:224
	ds_read_b128 v[68:71], v175 offset:240
	s_waitcnt lgkmcnt(9)
; __device__ __forceinline__ unsigned ck_cvt(float lo, float hi) { const f32x2 v = {lo, hi}; return __builtin_bit_cast(unsigned, __builtin_convertvector(v, ck_bf16x2_t)); }
; #define CK_COLLD(ss) do { _Pragma("unroll") for (int q_ = ((ss) + 1) / 4; q_ < 4; ++q_) cw[(ss)][q_] = *(const LAS f32x4*)(AabT + (ss) * 16 + 4 * q_); } while (0)
; __device__ __forceinline__ void scan_phase(LAS unsigned char* lds, const bf16_t* R, const bf16_t* Kb, const bf16_t* V, const bf16_t* WA, const float* k_k, const float* k_a, bf16_t* Y, int G, int bid, int tid) {
;     ...
;                 f32x4 cw[15][4];
;     ...
;                 CK_COLLD(0); CK_COLLD(1);
; #pragma unroll
;                 for (int s = 0; s < 15; ++s) {
;                     if (s + 2 < 15) CK_COLLD(s + 2);
;                     __builtin_amdgcn_sched_barrier(0);
; #pragma unroll
;                     for (int t = s + 1; t < 16; ++t) u[t] += cw[s][t >> 2][t & 3] * u[s];
;                 }
;     ...
;                 bf16x8 opu;
;                 { const bool g1 = (g & 1) != 0, g2 = (g & 2) != 0;
;                   const float a0 = g1 ? u[4] : u[0], a1 = g1 ? u[5] : u[1], a2 = g1 ? u[6] : u[2], a3 = g1 ? u[7] : u[3];
;                   const float b0 = g1 ? u[12] : u[8], b1 = g1 ? u[13] : u[9], b2 = g1 ? u[14] : u[10], b3 = g1 ? u[15] : u[11];
;                   opu = __builtin_bit_cast(bf16x8, (u32x4){ck_cvt(g2 ? b0 : a0, g2 ? b1 : a1), ck_cvt(g2 ? b2 : a2, g2 ? b3 : a3), 0u, 0u}); }
	v_fmac_f32_e32 v217, v13, v216
	v_pk_fma_f32 v[218:219], v[14:15], v[216:217], v[218:219] op_sel_hi:[1,0,1]
	v_pk_fma_f32 v[220:221], v[16:17], v[216:217], v[220:221] op_sel_hi:[1,0,1]
	v_pk_fma_f32 v[222:223], v[18:19], v[216:217], v[222:223] op_sel_hi:[1,0,1]
	v_pk_fma_f32 v[224:225], v[20:21], v[216:217], v[224:225] op_sel_hi:[1,0,1]
	v_pk_fma_f32 v[226:227], v[22:23], v[216:217], v[226:227] op_sel_hi:[1,0,1]
	v_pk_fma_f32 v[228:229], v[24:25], v[216:217], v[228:229] op_sel_hi:[1,0,1]
	v_pk_fma_f32 v[230:231], v[26:27], v[216:217], v[230:231] op_sel_hi:[1,0,1]
	ds_read_b128 v[72:75], v175 offset:272
	ds_read_b128 v[12:15], v175 offset:288
	ds_read_b128 v[16:19], v175 offset:304
	s_waitcnt lgkmcnt(8)
	v_pk_fma_f32 v[218:219], v[30:31], v[216:217], v[218:219] op_sel:[0,1,0] op_sel_hi:[1,1,1]
	v_pk_fma_f32 v[220:221], v[32:33], v[216:217], v[220:221] op_sel:[0,1,0] op_sel_hi:[1,1,1]
	v_pk_fma_f32 v[222:223], v[34:35], v[216:217], v[222:223] op_sel:[0,1,0] op_sel_hi:[1,1,1]
	v_pk_fma_f32 v[224:225], v[36:37], v[216:217], v[224:225] op_sel:[0,1,0] op_sel_hi:[1,1,1]
	v_pk_fma_f32 v[226:227], v[38:39], v[216:217], v[226:227] op_sel:[0,1,0] op_sel_hi:[1,1,1]
	v_pk_fma_f32 v[228:229], v[40:41], v[216:217], v[228:229] op_sel:[0,1,0] op_sel_hi:[1,1,1]
	v_pk_fma_f32 v[230:231], v[42:43], v[216:217], v[230:231] op_sel:[0,1,0] op_sel_hi:[1,1,1]
	ds_read_b128 v[20:23], v175 offset:336
	ds_read_b128 v[24:27], v175 offset:352
	ds_read_b128 v[28:31], v175 offset:368
	s_waitcnt lgkmcnt(6)
	v_fmac_f32_e32 v219, v47, v218
	v_pk_fma_f32 v[220:221], v[48:49], v[218:219], v[220:221] op_sel_hi:[1,0,1]
	v_pk_fma_f32 v[222:223], v[50:51], v[218:219], v[222:223] op_sel_hi:[1,0,1]
	v_pk_fma_f32 v[224:225], v[52:53], v[218:219], v[224:225] op_sel_hi:[1,0,1]
	v_pk_fma_f32 v[226:227], v[54:55], v[218:219], v[226:227] op_sel_hi:[1,0,1]
	v_pk_fma_f32 v[228:229], v[56:57], v[218:219], v[228:229] op_sel_hi:[1,0,1]
	v_pk_fma_f32 v[230:231], v[58:59], v[218:219], v[230:231] op_sel_hi:[1,0,1]
	ds_read_b128 v[32:35], v175 offset:400
	ds_read_b128 v[36:39], v175 offset:416
	ds_read_b128 v[40:43], v175 offset:432
	s_waitcnt lgkmcnt(6)
	v_pk_fma_f32 v[220:221], v[60:61], v[218:219], v[220:221] op_sel:[0,1,0] op_sel_hi:[1,1,1]
	v_pk_fma_f32 v[222:223], v[62:63], v[218:219], v[222:223] op_sel:[0,1,0] op_sel_hi:[1,1,1]
	v_pk_fma_f32 v[224:225], v[64:65], v[218:219], v[224:225] op_sel:[0,1,0] op_sel_hi:[1,1,1]
	v_pk_fma_f32 v[226:227], v[66:67], v[218:219], v[226:227] op_sel:[0,1,0] op_sel_hi:[1,1,1]
	v_pk_fma_f32 v[228:229], v[68:69], v[218:219], v[228:229] op_sel:[0,1,0] op_sel_hi:[1,1,1]
	v_pk_fma_f32 v[230:231], v[70:71], v[218:219], v[230:231] op_sel:[0,1,0] op_sel_hi:[1,1,1]
	ds_read_b128 v[44:47], v175 offset:480
	ds_read_b128 v[48:51], v175 offset:496
	s_waitcnt lgkmcnt(5)
	v_fmac_f32_e32 v221, v73, v220
	v_pk_fma_f32 v[222:223], v[74:75], v[220:221], v[222:223] op_sel_hi:[1,0,1]
	v_pk_fma_f32 v[224:225], v[12:13], v[220:221], v[224:225] op_sel_hi:[1,0,1]
	v_pk_fma_f32 v[226:227], v[14:15], v[220:221], v[226:227] op_sel_hi:[1,0,1]
	v_pk_fma_f32 v[228:229], v[16:17], v[220:221], v[228:229] op_sel_hi:[1,0,1]
	v_pk_fma_f32 v[230:231], v[18:19], v[220:221], v[230:231] op_sel_hi:[1,0,1]
	ds_read_b128 v[52:55], v175 offset:544
	ds_read_b128 v[56:59], v175 offset:560
	s_waitcnt lgkmcnt(4)
	v_pk_fma_f32 v[222:223], v[22:23], v[220:221], v[222:223] op_sel:[0,1,0] op_sel_hi:[1,1,1]
	v_pk_fma_f32 v[224:225], v[24:25], v[220:221], v[224:225] op_sel:[0,1,0] op_sel_hi:[1,1,1]
	v_pk_fma_f32 v[226:227], v[26:27], v[220:221], v[226:227] op_sel:[0,1,0] op_sel_hi:[1,1,1]
	v_pk_fma_f32 v[228:229], v[28:29], v[220:221], v[228:229] op_sel:[0,1,0] op_sel_hi:[1,1,1]
	v_pk_fma_f32 v[230:231], v[30:31], v[220:221], v[230:231] op_sel:[0,1,0] op_sel_hi:[1,1,1]
	ds_read_b128 v[60:63], v175 offset:608
	ds_read_b128 v[64:67], v175 offset:624
	s_waitcnt lgkmcnt(4)
	v_fmac_f32_e32 v223, v35, v222
	v_pk_fma_f32 v[224:225], v[36:37], v[222:223], v[224:225] op_sel_hi:[1,0,1]
	v_pk_fma_f32 v[226:227], v[38:39], v[222:223], v[226:227] op_sel_hi:[1,0,1]
	v_pk_fma_f32 v[228:229], v[40:41], v[222:223], v[228:229] op_sel_hi:[1,0,1]
	v_pk_fma_f32 v[230:231], v[42:43], v[222:223], v[230:231] op_sel_hi:[1,0,1]
	ds_read_b128 v[68:71], v175 offset:672
	ds_read_b128 v[72:75], v175 offset:688
	s_waitcnt lgkmcnt(4)
	v_pk_fma_f32 v[224:225], v[44:45], v[222:223], v[224:225] op_sel:[0,1,0] op_sel_hi:[1,1,1]
	v_pk_fma_f32 v[226:227], v[46:47], v[222:223], v[226:227] op_sel:[0,1,0] op_sel_hi:[1,1,1]
	v_pk_fma_f32 v[228:229], v[48:49], v[222:223], v[228:229] op_sel:[0,1,0] op_sel_hi:[1,1,1]
	v_pk_fma_f32 v[230:231], v[50:51], v[222:223], v[230:231] op_sel:[0,1,0] op_sel_hi:[1,1,1]
	ds_read_b128 v[12:15], v175 offset:752
	s_waitcnt lgkmcnt(3)
	v_fmac_f32_e32 v225, v53, v224
	v_pk_fma_f32 v[226:227], v[54:55], v[224:225], v[226:227] op_sel_hi:[1,0,1]
	v_pk_fma_f32 v[228:229], v[56:57], v[224:225], v[228:229] op_sel_hi:[1,0,1]
	v_pk_fma_f32 v[230:231], v[58:59], v[224:225], v[230:231] op_sel_hi:[1,0,1]
	ds_read_b128 v[16:19], v175 offset:816
	s_waitcnt lgkmcnt(2)
	v_pk_fma_f32 v[226:227], v[62:63], v[224:225], v[226:227] op_sel:[0,1,0] op_sel_hi:[1,1,1]
	v_pk_fma_f32 v[228:229], v[64:65], v[224:225], v[228:229] op_sel:[0,1,0] op_sel_hi:[1,1,1]
	v_pk_fma_f32 v[230:231], v[66:67], v[224:225], v[230:231] op_sel:[0,1,0] op_sel_hi:[1,1,1]
	ds_read_b128 v[20:23], v175 offset:880
	s_waitcnt lgkmcnt(2)
	v_fmac_f32_e32 v227, v71, v226
	v_pk_fma_f32 v[228:229], v[72:73], v[226:227], v[228:229] op_sel_hi:[1,0,1]
	v_pk_fma_f32 v[230:231], v[74:75], v[226:227], v[230:231] op_sel_hi:[1,0,1]
	ds_read_b128 v[24:27], v175 offset:944
	s_waitcnt lgkmcnt(2)
	v_pk_fma_f32 v[228:229], v[12:13], v[226:227], v[228:229] op_sel:[0,1,0] op_sel_hi:[1,1,1]
	v_pk_fma_f32 v[230:231], v[14:15], v[226:227], v[230:231] op_sel:[0,1,0] op_sel_hi:[1,1,1]
	s_waitcnt lgkmcnt(1)
	v_fmac_f32_e32 v229, v17, v228
	v_pk_fma_f32 v[230:231], v[18:19], v[228:229], v[230:231] op_sel_hi:[1,0,1]
	s_waitcnt lgkmcnt(0)
	v_pk_fma_f32 v[230:231], v[22:23], v[228:229], v[230:231] op_sel:[0,1,0] op_sel_hi:[1,1,1]
	v_fmac_f32_e32 v231, v27, v230
	v_cndmask_b32_e64 v84, v220, v216, s[4:5]
	v_cndmask_b32_e64 v96, v228, v224, s[4:5]
	v_cndmask_b32_e64 v84, v96, v84, s[6:7]
	v_cndmask_b32_e64 v85, v221, v217, s[4:5]
	v_cndmask_b32_e64 v96, v229, v225, s[4:5]
	v_cndmask_b32_e64 v85, v96, v85, s[6:7]
	v_cndmask_b32_e64 v86, v222, v218, s[4:5]
	v_cndmask_b32_e64 v96, v230, v226, s[4:5]
	v_cndmask_b32_e64 v86, v96, v86, s[6:7]
	v_cndmask_b32_e64 v87, v223, v219, s[4:5]
	v_cndmask_b32_e64 v96, v231, v227, s[4:5]
	v_cndmask_b32_e64 v87, v96, v87, s[6:7]
	ds_write_b128 v91, v[84:87]
	s_branch .LBB0_915

; #define LAS __attribute__((address_space(3)))
; __global__ void __launch_bounds__(NTHR, 2) hybrid_fwd(Args a) {
;     extern __shared__ __attribute__((aligned(16))) unsigned char lds_raw[];
;     LAS unsigned char* lds = (LAS unsigned char*)lds_raw;
	.amdhsa_kernel _Z10hybrid_fwd4Args
		.amdhsa_group_segment_fixed_size 0
		.amdhsa_private_segment_fixed_size 0
		.amdhsa_kernarg_size 472
		.amdhsa_user_sgpr_count 2
		.amdhsa_user_sgpr_dispatch_ptr 0
		.amdhsa_user_sgpr_queue_ptr 0
		.amdhsa_user_sgpr_kernarg_segment_ptr 1
		.amdhsa_user_sgpr_dispatch_id 0
		.amdhsa_user_sgpr_kernarg_preload_length 0
		.amdhsa_user_sgpr_kernarg_preload_offset 0
		.amdhsa_user_sgpr_private_segment_size 0
		.amdhsa_uses_dynamic_stack 0
		.amdhsa_enable_private_segment 0
		.amdhsa_system_sgpr_workgroup_id_x 1
		.amdhsa_system_sgpr_workgroup_id_y 0
		.amdhsa_system_sgpr_workgroup_id_z 0
		.amdhsa_system_sgpr_workgroup_info 0
		.amdhsa_system_vgpr_workitem_id 2
		.amdhsa_next_free_vgpr 255
		.amdhsa_next_free_sgpr 99
		.amdhsa_accum_offset 256
		.amdhsa_reserve_vcc 1
		.amdhsa_float_round_mode_32 0
		.amdhsa_float_round_mode_16_64 0
		.amdhsa_float_denorm_mode_32 3
		.amdhsa_float_denorm_mode_16_64 3
		.amdhsa_dx10_clamp 1
		.amdhsa_ieee_mode 1
		.amdhsa_fp16_overflow 0
		.amdhsa_tg_split 0
		.amdhsa_exception_fp_ieee_invalid_op 0
		.amdhsa_exception_fp_denorm_src 0
		.amdhsa_exception_fp_ieee_div_zero 0
		.amdhsa_exception_fp_ieee_overflow 0
		.amdhsa_exception_fp_ieee_underflow 0
		.amdhsa_exception_fp_ieee_inexact 0
		.amdhsa_exception_int_div_zero 0
	.end_amdhsa_kernel

; #define LAS __attribute__((address_space(3)))
; __global__ void __launch_bounds__(NTHR, 2) hybrid_fwd(Args a) {
;     extern __shared__ __attribute__((aligned(16))) unsigned char lds_raw[];
;     LAS unsigned char* lds = (LAS unsigned char*)lds_raw;
amdhsa.kernels:
  - .agpr_count:     0
    .args:
      - .offset:         0
        .size:           216
        .value_kind:     by_value
      - .offset:         216
        .size:           4
        .value_kind:     hidden_block_count_x
      - .offset:         220
        .size:           4
        .value_kind:     hidden_block_count_y
      - .offset:         224
        .size:           4
        .value_kind:     hidden_block_count_z
      - .offset:         228
        .size:           2
        .value_kind:     hidden_group_size_x
      - .offset:         230
        .size:           2
        .value_kind:     hidden_group_size_y
      - .offset:         232
        .size:           2
        .value_kind:     hidden_group_size_z
      - .offset:         234
        .size:           2
        .value_kind:     hidden_remainder_x
      - .offset:         236
        .size:           2
        .value_kind:     hidden_remainder_y
      - .offset:         238
        .size:           2
        .value_kind:     hidden_remainder_z
      - .offset:         256
        .size:           8
        .value_kind:     hidden_global_offset_x
      - .offset:         264
        .size:           8
        .value_kind:     hidden_global_offset_y
      - .offset:         272
        .size:           8
        .value_kind:     hidden_global_offset_z
      - .offset:         280
        .size:           2
        .value_kind:     hidden_grid_dims
      - .offset:         304
        .size:           8
        .value_kind:     hidden_multigrid_sync_arg
      - .offset:         336
        .size:           4
        .value_kind:     hidden_dynamic_lds_size
    .group_segment_fixed_size: 0
    .kernarg_segment_align: 8
    .kernarg_segment_size: 472
    .language:       OpenCL C
    .language_version:
      - 2
      - 0
    .max_flat_workgroup_size: 512
    .name:           _Z10hybrid_fwd4Args
    .private_segment_fixed_size: 0
    .sgpr_count:     105
    .sgpr_spill_count: 13
    .symbol:         _Z10hybrid_fwd4Args.kd
    .uniform_work_group_size: 1
    .uses_dynamic_stack: false
    .vgpr_count:     255
    .vgpr_spill_count: 0
    .wavefront_size: 64
